# mod_item GEMV fully unrolled (4 trips/half) with next-trip ada_w rows prefetched into alternate register set; waits relaxed to vmcnt(8)
# speedup vs baseline: 1.0206x; 1.0034x over previous
.LBB0_147:
	v_lshl_add_u64 v[106:107], v[76:77], 0, s[68:69]
	global_load_dwordx4 v[216:219], v[106:107], off
	v_add_co_u32_e32 v212, vcc, 0x6000, v106
	s_nop 1
	v_addc_co_u32_e32 v213, vcc, 0, v107, vcc
	global_load_dwordx4 v[220:223], v[212:213], off
	v_add_co_u32_e32 v212, vcc, 0xc000, v106
	s_nop 1
	v_addc_co_u32_e32 v213, vcc, 0, v107, vcc
	global_load_dwordx4 v[224:227], v[212:213], off
	v_add_co_u32_e32 v212, vcc, 0x12000, v106
	s_nop 1
	v_addc_co_u32_e32 v213, vcc, 0, v107, vcc
	global_load_dwordx4 v[228:231], v[212:213], off
	v_add_co_u32_e32 v212, vcc, 0x18000, v106
	s_nop 1
	v_addc_co_u32_e32 v213, vcc, 0, v107, vcc
	global_load_dwordx4 v[232:235], v[212:213], off
	v_add_co_u32_e32 v212, vcc, 0x1e000, v106
	s_nop 1
	v_addc_co_u32_e32 v213, vcc, 0, v107, vcc
	global_load_dwordx4 v[236:239], v[212:213], off
	v_add_co_u32_e32 v212, vcc, 0x24000, v106
	s_nop 1
	v_addc_co_u32_e32 v213, vcc, 0, v107, vcc
	global_load_dwordx4 v[240:243], v[212:213], off
	v_add_co_u32_e32 v212, vcc, 0x2a000, v106
	s_nop 1
	v_addc_co_u32_e32 v213, vcc, 0, v107, vcc
	global_load_dwordx4 v[244:247], v[212:213], off
	v_add_co_u32_e32 v212, vcc, 0x30000, v106
	s_nop 1
	v_addc_co_u32_e32 v213, vcc, 0, v107, vcc
	global_load_dwordx4 v[180:183], v[212:213], off
	v_add_co_u32_e32 v212, vcc, 0x36000, v106
	s_nop 1
	v_addc_co_u32_e32 v213, vcc, 0, v107, vcc
	global_load_dwordx4 v[184:187], v[212:213], off
	v_add_co_u32_e32 v212, vcc, 0x3c000, v106
	s_nop 1
	v_addc_co_u32_e32 v213, vcc, 0, v107, vcc
	global_load_dwordx4 v[188:191], v[212:213], off
	v_add_co_u32_e32 v212, vcc, 0x42000, v106
	s_nop 1
	v_addc_co_u32_e32 v213, vcc, 0, v107, vcc
	global_load_dwordx4 v[192:195], v[212:213], off
	v_add_co_u32_e32 v212, vcc, 0x48000, v106
	s_nop 1
	v_addc_co_u32_e32 v213, vcc, 0, v107, vcc
	global_load_dwordx4 v[196:199], v[212:213], off
	v_add_co_u32_e32 v212, vcc, 0x4e000, v106
	s_nop 1
	v_addc_co_u32_e32 v213, vcc, 0, v107, vcc
	global_load_dwordx4 v[200:203], v[212:213], off
	v_add_co_u32_e32 v212, vcc, 0x54000, v106
	s_nop 1
	v_addc_co_u32_e32 v213, vcc, 0, v107, vcc
	global_load_dwordx4 v[204:207], v[212:213], off
	v_add_co_u32_e32 v212, vcc, 0x5a000, v106
	s_nop 1
	v_addc_co_u32_e32 v213, vcc, 0, v107, vcc
	global_load_dwordx4 v[208:211], v[212:213], off
	ds_read_b128 v[4:7], v72
	ds_read_b128 v[0:3], v72 offset:16
	s_mov_b32 s24, 0xc000
	s_add_u32 s68, s68, 0x30000
	s_addc_u32 s69, s69, 0
	s_cmp_eq_u32 s68, 0xc0000
	s_waitcnt vmcnt(8) lgkmcnt(1)
	v_mov_b64_e32 v[112:113], v[216:217]
	v_mov_b64_e32 v[114:115], v[218:219]
	v_pk_fma_f32 v[108:109], v[114:115], v[4:5], v[8:9] op_sel_hi:[1,0,1]
	ds_read_b128 v[8:11], v72 offset:2048
	v_pk_fma_f32 v[104:105], v[112:113], v[4:5], v[104:105] op_sel_hi:[1,0,1]
	s_waitcnt lgkmcnt(0)
	v_pk_fma_f32 v[116:117], v[114:115], v[8:9], v[12:13] op_sel_hi:[1,0,1]
	ds_read_b128 v[12:15], v72 offset:4096
	v_pk_fma_f32 v[102:103], v[112:113], v[8:9], v[102:103] op_sel_hi:[1,0,1]
	s_waitcnt lgkmcnt(0)
	v_pk_fma_f32 v[118:119], v[114:115], v[12:13], v[16:17] op_sel_hi:[1,0,1]
	ds_read_b128 v[16:19], v72 offset:6144
	v_pk_fma_f32 v[100:101], v[112:113], v[12:13], v[100:101] op_sel_hi:[1,0,1]
	s_waitcnt lgkmcnt(0)
	v_pk_fma_f32 v[120:121], v[114:115], v[16:17], v[20:21] op_sel_hi:[1,0,1]
	ds_read_b128 v[20:23], v72 offset:8192
	v_pk_fma_f32 v[98:99], v[112:113], v[16:17], v[98:99] op_sel_hi:[1,0,1]
	s_waitcnt lgkmcnt(0)
	v_pk_fma_f32 v[122:123], v[114:115], v[20:21], v[24:25] op_sel_hi:[1,0,1]
	ds_read_b128 v[24:27], v72 offset:10240
	v_pk_fma_f32 v[96:97], v[112:113], v[20:21], v[96:97] op_sel_hi:[1,0,1]
	s_waitcnt lgkmcnt(0)
	v_pk_fma_f32 v[124:125], v[114:115], v[24:25], v[28:29] op_sel_hi:[1,0,1]
	ds_read_b128 v[28:31], v72 offset:12288
	v_pk_fma_f32 v[94:95], v[112:113], v[24:25], v[94:95] op_sel_hi:[1,0,1]
	s_waitcnt lgkmcnt(0)
	v_pk_fma_f32 v[126:127], v[114:115], v[28:29], v[32:33] op_sel_hi:[1,0,1]
	ds_read_b128 v[32:35], v72 offset:14336
	v_pk_fma_f32 v[92:93], v[112:113], v[28:29], v[92:93] op_sel_hi:[1,0,1]
	s_waitcnt lgkmcnt(0)
	v_pk_fma_f32 v[128:129], v[114:115], v[32:33], v[36:37] op_sel_hi:[1,0,1]
	ds_read_b128 v[36:39], v72 offset:16384
	v_pk_fma_f32 v[90:91], v[112:113], v[32:33], v[90:91] op_sel_hi:[1,0,1]
	s_waitcnt lgkmcnt(0)
	v_pk_fma_f32 v[130:131], v[114:115], v[36:37], v[40:41] op_sel_hi:[1,0,1]
	ds_read_b128 v[40:43], v72 offset:18432
	v_pk_fma_f32 v[88:89], v[112:113], v[36:37], v[88:89] op_sel_hi:[1,0,1]
	s_waitcnt lgkmcnt(0)
	v_pk_fma_f32 v[132:133], v[114:115], v[40:41], v[44:45] op_sel_hi:[1,0,1]
	ds_read_b128 v[44:47], v72 offset:20480
	v_pk_fma_f32 v[86:87], v[112:113], v[40:41], v[86:87] op_sel_hi:[1,0,1]
	s_waitcnt lgkmcnt(0)
	v_pk_fma_f32 v[134:135], v[114:115], v[44:45], v[48:49] op_sel_hi:[1,0,1]
	ds_read_b128 v[48:51], v72 offset:22528
	v_pk_fma_f32 v[84:85], v[112:113], v[44:45], v[84:85] op_sel_hi:[1,0,1]
	s_waitcnt lgkmcnt(0)
	v_pk_fma_f32 v[136:137], v[114:115], v[48:49], v[52:53] op_sel_hi:[1,0,1]
	ds_read_b128 v[52:55], v72 offset:24576
	v_pk_fma_f32 v[82:83], v[112:113], v[48:49], v[82:83] op_sel_hi:[1,0,1]
	s_waitcnt lgkmcnt(0)
	v_pk_fma_f32 v[146:147], v[112:113], v[52:53], v[58:59] op_sel_hi:[1,0,1]
	v_pk_fma_f32 v[148:149], v[114:115], v[52:53], v[56:57] op_sel_hi:[1,0,1]
	ds_read_b128 v[56:59], v72 offset:26624
	s_waitcnt lgkmcnt(0)
	v_pk_fma_f32 v[150:151], v[112:113], v[56:57], v[62:63] op_sel_hi:[1,0,1]
	v_pk_fma_f32 v[152:153], v[114:115], v[56:57], v[60:61] op_sel_hi:[1,0,1]
	ds_read_b128 v[60:63], v72 offset:28672
	s_waitcnt lgkmcnt(0)
	v_pk_fma_f32 v[154:155], v[112:113], v[60:61], v[66:67] op_sel_hi:[1,0,1]
	v_pk_fma_f32 v[156:157], v[114:115], v[60:61], v[64:65] op_sel_hi:[1,0,1]
	ds_read_b128 v[64:67], v72 offset:30720
	s_waitcnt lgkmcnt(0)
	v_pk_fma_f32 v[158:159], v[112:113], v[64:65], v[70:71] op_sel_hi:[1,0,1]
	v_pk_fma_f32 v[160:161], v[114:115], v[64:65], v[68:69] op_sel_hi:[1,0,1]
	ds_read_b128 v[68:71], v72 offset:32768
	s_waitcnt lgkmcnt(0)
	v_pk_fma_f32 v[114:115], v[114:115], v[68:69], v[78:79] op_sel_hi:[1,0,1]
	v_add_co_u32_e32 v78, vcc, s75, v106
	v_pk_fma_f32 v[112:113], v[112:113], v[68:69], v[80:81] op_sel_hi:[1,0,1]
	s_nop 0
	v_addc_co_u32_e32 v79, vcc, 0, v107, vcc
	s_waitcnt vmcnt(8)
	v_mov_b64_e32 v[78:79], v[220:221]
	v_mov_b64_e32 v[80:81], v[222:223]
	v_pk_fma_f32 v[104:105], v[78:79], v[4:5], v[104:105] op_sel:[0,1,0]
	v_pk_fma_f32 v[4:5], v[80:81], v[4:5], v[108:109] op_sel:[0,1,0]
	v_pk_fma_f32 v[102:103], v[78:79], v[8:9], v[102:103] op_sel:[0,1,0]
	v_pk_fma_f32 v[8:9], v[80:81], v[8:9], v[116:117] op_sel:[0,1,0]
	v_pk_fma_f32 v[100:101], v[78:79], v[12:13], v[100:101] op_sel:[0,1,0]
	v_pk_fma_f32 v[12:13], v[80:81], v[12:13], v[118:119] op_sel:[0,1,0]
	v_pk_fma_f32 v[98:99], v[78:79], v[16:17], v[98:99] op_sel:[0,1,0]
	v_pk_fma_f32 v[16:17], v[80:81], v[16:17], v[120:121] op_sel:[0,1,0]
	v_pk_fma_f32 v[96:97], v[78:79], v[20:21], v[96:97] op_sel:[0,1,0]
	v_pk_fma_f32 v[94:95], v[78:79], v[24:25], v[94:95] op_sel:[0,1,0]
	v_pk_fma_f32 v[92:93], v[78:79], v[28:29], v[92:93] op_sel:[0,1,0]
	v_pk_fma_f32 v[90:91], v[78:79], v[32:33], v[90:91] op_sel:[0,1,0]
	v_pk_fma_f32 v[88:89], v[78:79], v[36:37], v[88:89] op_sel:[0,1,0]
	v_pk_fma_f32 v[86:87], v[78:79], v[40:41], v[86:87] op_sel:[0,1,0]
	v_pk_fma_f32 v[84:85], v[78:79], v[44:45], v[84:85] op_sel:[0,1,0]
	v_pk_fma_f32 v[82:83], v[78:79], v[48:49], v[82:83] op_sel:[0,1,0]
	v_pk_fma_f32 v[108:109], v[78:79], v[52:53], v[146:147] op_sel:[0,1,0]
	v_pk_fma_f32 v[116:117], v[78:79], v[56:57], v[150:151] op_sel:[0,1,0]
	v_pk_fma_f32 v[118:119], v[78:79], v[60:61], v[154:155] op_sel:[0,1,0]
	v_pk_fma_f32 v[120:121], v[78:79], v[64:65], v[158:159] op_sel:[0,1,0]
	v_pk_fma_f32 v[112:113], v[78:79], v[68:69], v[112:113] op_sel:[0,1,0]
	v_add_co_u32_e32 v78, vcc, s24, v106
	v_pk_fma_f32 v[20:21], v[80:81], v[20:21], v[122:123] op_sel:[0,1,0]
	s_nop 0
	v_addc_co_u32_e32 v79, vcc, 0, v107, vcc
	v_pk_fma_f32 v[24:25], v[80:81], v[24:25], v[124:125] op_sel:[0,1,0]
	v_pk_fma_f32 v[28:29], v[80:81], v[28:29], v[126:127] op_sel:[0,1,0]
	v_pk_fma_f32 v[32:33], v[80:81], v[32:33], v[128:129] op_sel:[0,1,0]
	v_pk_fma_f32 v[36:37], v[80:81], v[36:37], v[130:131] op_sel:[0,1,0]
	v_pk_fma_f32 v[40:41], v[80:81], v[40:41], v[132:133] op_sel:[0,1,0]
	v_pk_fma_f32 v[44:45], v[80:81], v[44:45], v[134:135] op_sel:[0,1,0]
	v_pk_fma_f32 v[48:49], v[80:81], v[48:49], v[136:137] op_sel:[0,1,0]
	v_pk_fma_f32 v[52:53], v[80:81], v[52:53], v[148:149] op_sel:[0,1,0]
	v_pk_fma_f32 v[56:57], v[80:81], v[56:57], v[152:153] op_sel:[0,1,0]
	v_pk_fma_f32 v[60:61], v[80:81], v[60:61], v[156:157] op_sel:[0,1,0]
	v_pk_fma_f32 v[64:65], v[80:81], v[64:65], v[160:161] op_sel:[0,1,0]
	v_pk_fma_f32 v[68:69], v[80:81], v[68:69], v[114:115] op_sel:[0,1,0]
	s_mov_b32 s24, 0x12000
	s_waitcnt vmcnt(8)
	v_mov_b64_e32 v[78:79], v[224:225]
	v_mov_b64_e32 v[80:81], v[226:227]
	v_pk_fma_f32 v[122:123], v[80:81], v[14:15], v[12:13] op_sel_hi:[1,0,1]
	v_add_co_u32_e32 v12, vcc, s24, v106
	v_pk_fma_f32 v[156:157], v[78:79], v[70:71], v[112:113] op_sel_hi:[1,0,1]
	s_nop 0
	v_addc_co_u32_e32 v13, vcc, 0, v107, vcc
	v_pk_fma_f32 v[104:105], v[78:79], v[6:7], v[104:105] op_sel_hi:[1,0,1]
	v_pk_fma_f32 v[4:5], v[80:81], v[6:7], v[4:5] op_sel_hi:[1,0,1]
	v_mov_b32_e32 v6, v7
	v_pk_fma_f32 v[102:103], v[78:79], v[10:11], v[102:103] op_sel_hi:[1,0,1]
	v_pk_fma_f32 v[8:9], v[80:81], v[10:11], v[8:9] op_sel_hi:[1,0,1]
	v_pk_fma_f32 v[100:101], v[78:79], v[14:15], v[100:101] op_sel_hi:[1,0,1]
	v_pk_fma_f32 v[150:151], v[78:79], v[54:55], v[108:109] op_sel_hi:[1,0,1]
	v_pk_fma_f32 v[98:99], v[78:79], v[18:19], v[98:99] op_sel_hi:[1,0,1]
	v_pk_fma_f32 v[124:125], v[80:81], v[18:19], v[16:17] op_sel_hi:[1,0,1]
	v_pk_fma_f32 v[96:97], v[78:79], v[22:23], v[96:97] op_sel_hi:[1,0,1]
	v_pk_fma_f32 v[126:127], v[80:81], v[22:23], v[20:21] op_sel_hi:[1,0,1]
	v_pk_fma_f32 v[94:95], v[78:79], v[26:27], v[94:95] op_sel_hi:[1,0,1]
	v_pk_fma_f32 v[128:129], v[80:81], v[26:27], v[24:25] op_sel_hi:[1,0,1]
	v_pk_fma_f32 v[92:93], v[78:79], v[30:31], v[92:93] op_sel_hi:[1,0,1]
	v_pk_fma_f32 v[130:131], v[80:81], v[30:31], v[28:29] op_sel_hi:[1,0,1]
	v_pk_fma_f32 v[90:91], v[78:79], v[34:35], v[90:91] op_sel_hi:[1,0,1]
	v_pk_fma_f32 v[132:133], v[80:81], v[34:35], v[32:33] op_sel_hi:[1,0,1]
	v_pk_fma_f32 v[88:89], v[78:79], v[38:39], v[88:89] op_sel_hi:[1,0,1]
	v_pk_fma_f32 v[134:135], v[80:81], v[38:39], v[36:37] op_sel_hi:[1,0,1]
	v_pk_fma_f32 v[86:87], v[78:79], v[42:43], v[86:87] op_sel_hi:[1,0,1]
	v_pk_fma_f32 v[136:137], v[80:81], v[42:43], v[40:41] op_sel_hi:[1,0,1]
	v_pk_fma_f32 v[84:85], v[78:79], v[46:47], v[84:85] op_sel_hi:[1,0,1]
	v_pk_fma_f32 v[146:147], v[80:81], v[46:47], v[44:45] op_sel_hi:[1,0,1]
	v_pk_fma_f32 v[82:83], v[78:79], v[50:51], v[82:83] op_sel_hi:[1,0,1]
	v_pk_fma_f32 v[148:149], v[80:81], v[50:51], v[48:49] op_sel_hi:[1,0,1]
	v_pk_fma_f32 v[152:153], v[80:81], v[54:55], v[52:53] op_sel_hi:[1,0,1]
	v_pk_fma_f32 v[116:117], v[78:79], v[58:59], v[116:117] op_sel_hi:[1,0,1]
	v_pk_fma_f32 v[56:57], v[80:81], v[58:59], v[56:57] op_sel_hi:[1,0,1]
	v_pk_fma_f32 v[118:119], v[78:79], v[62:63], v[118:119] op_sel_hi:[1,0,1]
	v_pk_fma_f32 v[60:61], v[80:81], v[62:63], v[60:61] op_sel_hi:[1,0,1]
	v_pk_fma_f32 v[120:121], v[78:79], v[66:67], v[120:121] op_sel_hi:[1,0,1]
	v_pk_fma_f32 v[154:155], v[80:81], v[66:67], v[64:65] op_sel_hi:[1,0,1]
	v_pk_fma_f32 v[158:159], v[80:81], v[70:71], v[68:69] op_sel_hi:[1,0,1]
	s_mov_b32 s24, 0x18000
	s_waitcnt vmcnt(8)
	v_mov_b64_e32 v[112:113], v[228:229]
	v_mov_b64_e32 v[114:115], v[230:231]
	v_pk_fma_f32 v[162:163], v[114:115], v[6:7], v[4:5] op_sel_hi:[1,0,1]
	v_mov_b32_e32 v4, v11
	v_pk_fma_f32 v[12:13], v[112:113], v[4:5], v[102:103] op_sel_hi:[1,0,1]
	v_pk_fma_f32 v[108:109], v[114:115], v[4:5], v[8:9] op_sel_hi:[1,0,1]
	v_mov_b32_e32 v4, v15
	v_pk_fma_f32 v[160:161], v[112:113], v[6:7], v[104:105] op_sel_hi:[1,0,1]
	v_pk_fma_f32 v[16:17], v[112:113], v[4:5], v[100:101] op_sel_hi:[1,0,1]
	v_pk_fma_f32 v[104:105], v[114:115], v[4:5], v[122:123] op_sel_hi:[1,0,1]
	v_mov_b32_e32 v4, v19
	v_pk_fma_f32 v[20:21], v[112:113], v[4:5], v[98:99] op_sel_hi:[1,0,1]
	v_pk_fma_f32 v[102:103], v[114:115], v[4:5], v[124:125] op_sel_hi:[1,0,1]
	v_mov_b32_e32 v4, v23
	v_pk_fma_f32 v[24:25], v[112:113], v[4:5], v[96:97] op_sel_hi:[1,0,1]
	v_pk_fma_f32 v[100:101], v[114:115], v[4:5], v[126:127] op_sel_hi:[1,0,1]
	v_mov_b32_e32 v4, v27
	v_pk_fma_f32 v[28:29], v[112:113], v[4:5], v[94:95] op_sel_hi:[1,0,1]
	v_pk_fma_f32 v[98:99], v[114:115], v[4:5], v[128:129] op_sel_hi:[1,0,1]
	v_mov_b32_e32 v4, v31
	v_pk_fma_f32 v[32:33], v[112:113], v[4:5], v[92:93] op_sel_hi:[1,0,1]
	v_pk_fma_f32 v[96:97], v[114:115], v[4:5], v[130:131] op_sel_hi:[1,0,1]
	v_mov_b32_e32 v4, v35
	v_pk_fma_f32 v[36:37], v[112:113], v[4:5], v[90:91] op_sel_hi:[1,0,1]
	v_pk_fma_f32 v[94:95], v[114:115], v[4:5], v[132:133] op_sel_hi:[1,0,1]
	v_mov_b32_e32 v4, v39
	v_pk_fma_f32 v[40:41], v[112:113], v[4:5], v[88:89] op_sel_hi:[1,0,1]
	v_pk_fma_f32 v[92:93], v[114:115], v[4:5], v[134:135] op_sel_hi:[1,0,1]
	v_mov_b32_e32 v4, v43
	v_pk_fma_f32 v[44:45], v[112:113], v[4:5], v[86:87] op_sel_hi:[1,0,1]
	v_pk_fma_f32 v[90:91], v[114:115], v[4:5], v[136:137] op_sel_hi:[1,0,1]
	v_mov_b32_e32 v4, v47
	v_pk_fma_f32 v[48:49], v[112:113], v[4:5], v[84:85] op_sel_hi:[1,0,1]
	v_pk_fma_f32 v[88:89], v[114:115], v[4:5], v[146:147] op_sel_hi:[1,0,1]
	v_mov_b32_e32 v4, v51
	v_pk_fma_f32 v[52:53], v[112:113], v[4:5], v[82:83] op_sel_hi:[1,0,1]
	v_pk_fma_f32 v[86:87], v[114:115], v[4:5], v[148:149] op_sel_hi:[1,0,1]
	v_mov_b32_e32 v4, v55
	v_pk_fma_f32 v[82:83], v[112:113], v[4:5], v[150:151] op_sel_hi:[1,0,1]
	v_pk_fma_f32 v[84:85], v[114:115], v[4:5], v[152:153] op_sel_hi:[1,0,1]
	v_mov_b32_e32 v4, v59
	v_pk_fma_f32 v[78:79], v[112:113], v[4:5], v[116:117] op_sel_hi:[1,0,1]
	v_pk_fma_f32 v[80:81], v[114:115], v[4:5], v[56:57] op_sel_hi:[1,0,1]
	v_mov_b32_e32 v4, v63
	v_pk_fma_f32 v[64:65], v[112:113], v[4:5], v[118:119] op_sel_hi:[1,0,1]
	v_pk_fma_f32 v[68:69], v[114:115], v[4:5], v[60:61] op_sel_hi:[1,0,1]
	v_mov_b32_e32 v4, v67
	v_pk_fma_f32 v[60:61], v[112:113], v[4:5], v[120:121] op_sel_hi:[1,0,1]
	v_pk_fma_f32 v[62:63], v[114:115], v[4:5], v[154:155] op_sel_hi:[1,0,1]
	v_mov_b32_e32 v4, v71
	v_pk_fma_f32 v[56:57], v[112:113], v[4:5], v[156:157] op_sel_hi:[1,0,1]
	v_pk_fma_f32 v[58:59], v[114:115], v[4:5], v[158:159] op_sel_hi:[1,0,1]
	v_add_co_u32_e32 v4, vcc, s24, v106
	ds_read_b128 v[8:11], v72 offset:2064
	ds_read_b128 v[120:123], v72 offset:32784
	v_addc_co_u32_e32 v5, vcc, 0, v107, vcc
	ds_read_b128 v[112:115], v72 offset:26640
	ds_read_b128 v[116:119], v72 offset:30736
	s_mov_b32 s24, 0x1e000
	s_waitcnt vmcnt(8) lgkmcnt(3)
	v_mov_b64_e32 v[4:5], v[232:233]
	v_mov_b64_e32 v[6:7], v[234:235]
	v_pk_fma_f32 v[124:125], v[4:5], v[8:9], v[12:13] op_sel_hi:[1,0,1]
	ds_read_b128 v[12:15], v72 offset:4112
	s_waitcnt lgkmcnt(2)
	v_pk_fma_f32 v[154:155], v[4:5], v[112:113], v[78:79] op_sel_hi:[1,0,1]
	v_pk_fma_f32 v[156:157], v[6:7], v[112:113], v[80:81] op_sel_hi:[1,0,1]
	ds_read_b128 v[78:81], v72 offset:28688
	v_pk_fma_f32 v[66:67], v[4:5], v[0:1], v[160:161] op_sel_hi:[1,0,1]
	s_waitcnt lgkmcnt(1)
	v_pk_fma_f32 v[126:127], v[4:5], v[12:13], v[16:17] op_sel_hi:[1,0,1]
	ds_read_b128 v[16:19], v72 offset:6160
	v_pk_fma_f32 v[60:61], v[4:5], v[116:117], v[60:61] op_sel_hi:[1,0,1]
	s_waitcnt lgkmcnt(1)
	v_pk_fma_f32 v[64:65], v[4:5], v[78:79], v[64:65] op_sel_hi:[1,0,1]
	v_pk_fma_f32 v[56:57], v[4:5], v[120:121], v[56:57] op_sel_hi:[1,0,1]
	v_pk_fma_f32 v[70:71], v[6:7], v[0:1], v[162:163] op_sel_hi:[1,0,1]
	s_waitcnt lgkmcnt(0)
	v_pk_fma_f32 v[128:129], v[4:5], v[16:17], v[20:21] op_sel_hi:[1,0,1]
	ds_read_b128 v[20:23], v72 offset:8208
	v_pk_fma_f32 v[108:109], v[6:7], v[8:9], v[108:109] op_sel_hi:[1,0,1]
	v_pk_fma_f32 v[104:105], v[6:7], v[12:13], v[104:105] op_sel_hi:[1,0,1]
	v_pk_fma_f32 v[102:103], v[6:7], v[16:17], v[102:103] op_sel_hi:[1,0,1]
	v_pk_fma_f32 v[68:69], v[6:7], v[78:79], v[68:69] op_sel_hi:[1,0,1]
	s_waitcnt lgkmcnt(0)
	v_pk_fma_f32 v[130:131], v[4:5], v[20:21], v[24:25] op_sel_hi:[1,0,1]
	ds_read_b128 v[24:27], v72 offset:10256
	v_pk_fma_f32 v[100:101], v[6:7], v[20:21], v[100:101] op_sel_hi:[1,0,1]
	v_pk_fma_f32 v[62:63], v[6:7], v[116:117], v[62:63] op_sel_hi:[1,0,1]
	v_pk_fma_f32 v[58:59], v[6:7], v[120:121], v[58:59] op_sel_hi:[1,0,1]
	s_waitcnt lgkmcnt(0)
	v_pk_fma_f32 v[132:133], v[4:5], v[24:25], v[28:29] op_sel_hi:[1,0,1]
	ds_read_b128 v[28:31], v72 offset:12304
	v_pk_fma_f32 v[98:99], v[6:7], v[24:25], v[98:99] op_sel_hi:[1,0,1]
	s_waitcnt lgkmcnt(0)
	v_pk_fma_f32 v[134:135], v[4:5], v[28:29], v[32:33] op_sel_hi:[1,0,1]
	ds_read_b128 v[32:35], v72 offset:14352
	v_pk_fma_f32 v[96:97], v[6:7], v[28:29], v[96:97] op_sel_hi:[1,0,1]
	s_waitcnt lgkmcnt(0)
	v_pk_fma_f32 v[136:137], v[4:5], v[32:33], v[36:37] op_sel_hi:[1,0,1]
	ds_read_b128 v[36:39], v72 offset:16400
	v_pk_fma_f32 v[94:95], v[6:7], v[32:33], v[94:95] op_sel_hi:[1,0,1]
	s_waitcnt lgkmcnt(0)
	v_pk_fma_f32 v[146:147], v[4:5], v[36:37], v[40:41] op_sel_hi:[1,0,1]
	ds_read_b128 v[40:43], v72 offset:18448
	v_pk_fma_f32 v[92:93], v[6:7], v[36:37], v[92:93] op_sel_hi:[1,0,1]
	s_waitcnt lgkmcnt(0)
	v_pk_fma_f32 v[148:149], v[4:5], v[40:41], v[44:45] op_sel_hi:[1,0,1]
	ds_read_b128 v[44:47], v72 offset:20496
	v_pk_fma_f32 v[90:91], v[6:7], v[40:41], v[90:91] op_sel_hi:[1,0,1]
	s_waitcnt lgkmcnt(0)
	v_pk_fma_f32 v[150:151], v[4:5], v[44:45], v[48:49] op_sel_hi:[1,0,1]
	ds_read_b128 v[48:51], v72 offset:22544
	v_pk_fma_f32 v[88:89], v[6:7], v[44:45], v[88:89] op_sel_hi:[1,0,1]
	s_waitcnt lgkmcnt(0)
	v_pk_fma_f32 v[152:153], v[4:5], v[48:49], v[52:53] op_sel_hi:[1,0,1]
	ds_read_b128 v[52:55], v72 offset:24592
	v_pk_fma_f32 v[86:87], v[6:7], v[48:49], v[86:87] op_sel_hi:[1,0,1]
	v_add_u32_e32 v72, 32, v72
	s_waitcnt lgkmcnt(0)
	v_pk_fma_f32 v[82:83], v[4:5], v[52:53], v[82:83] op_sel_hi:[1,0,1]
	v_add_co_u32_e32 v4, vcc, s24, v106
	v_pk_fma_f32 v[84:85], v[6:7], v[52:53], v[84:85] op_sel_hi:[1,0,1]
	s_nop 0
	v_addc_co_u32_e32 v5, vcc, 0, v107, vcc
	s_mov_b32 s24, 0x24000
	s_waitcnt vmcnt(8)
	v_mov_b64_e32 v[4:5], v[236:237]
	v_mov_b64_e32 v[6:7], v[238:239]
	v_pk_fma_f32 v[66:67], v[4:5], v[0:1], v[66:67] op_sel:[0,1,0]
	v_pk_fma_f32 v[0:1], v[6:7], v[0:1], v[70:71] op_sel:[0,1,0]
	v_pk_fma_f32 v[70:71], v[4:5], v[8:9], v[124:125] op_sel:[0,1,0]
	v_pk_fma_f32 v[8:9], v[6:7], v[8:9], v[108:109] op_sel:[0,1,0]
	v_pk_fma_f32 v[108:109], v[4:5], v[12:13], v[126:127] op_sel:[0,1,0]
	v_pk_fma_f32 v[12:13], v[6:7], v[12:13], v[104:105] op_sel:[0,1,0]
	v_pk_fma_f32 v[104:105], v[4:5], v[16:17], v[128:129] op_sel:[0,1,0]
	v_pk_fma_f32 v[16:17], v[6:7], v[16:17], v[102:103] op_sel:[0,1,0]
	v_pk_fma_f32 v[102:103], v[4:5], v[20:21], v[130:131] op_sel:[0,1,0]
	v_pk_fma_f32 v[20:21], v[6:7], v[20:21], v[100:101] op_sel:[0,1,0]
	v_pk_fma_f32 v[100:101], v[4:5], v[24:25], v[132:133] op_sel:[0,1,0]
	v_pk_fma_f32 v[24:25], v[6:7], v[24:25], v[98:99] op_sel:[0,1,0]
	v_pk_fma_f32 v[98:99], v[4:5], v[28:29], v[134:135] op_sel:[0,1,0]
	v_pk_fma_f32 v[28:29], v[6:7], v[28:29], v[96:97] op_sel:[0,1,0]
	v_pk_fma_f32 v[96:97], v[4:5], v[32:33], v[136:137] op_sel:[0,1,0]
	v_pk_fma_f32 v[32:33], v[6:7], v[32:33], v[94:95] op_sel:[0,1,0]
	v_pk_fma_f32 v[94:95], v[4:5], v[36:37], v[146:147] op_sel:[0,1,0]
	v_pk_fma_f32 v[36:37], v[6:7], v[36:37], v[92:93] op_sel:[0,1,0]
	v_pk_fma_f32 v[92:93], v[4:5], v[40:41], v[148:149] op_sel:[0,1,0]
	v_pk_fma_f32 v[40:41], v[6:7], v[40:41], v[90:91] op_sel:[0,1,0]
	v_pk_fma_f32 v[90:91], v[4:5], v[44:45], v[150:151] op_sel:[0,1,0]
	v_pk_fma_f32 v[44:45], v[6:7], v[44:45], v[88:89] op_sel:[0,1,0]
	v_pk_fma_f32 v[88:89], v[4:5], v[48:49], v[152:153] op_sel:[0,1,0]
	v_pk_fma_f32 v[82:83], v[4:5], v[52:53], v[82:83] op_sel:[0,1,0]
	v_pk_fma_f32 v[52:53], v[6:7], v[52:53], v[84:85] op_sel:[0,1,0]
	v_pk_fma_f32 v[84:85], v[4:5], v[112:113], v[154:155] op_sel:[0,1,0]
	v_pk_fma_f32 v[64:65], v[4:5], v[78:79], v[64:65] op_sel:[0,1,0]
	v_pk_fma_f32 v[60:61], v[4:5], v[116:117], v[60:61] op_sel:[0,1,0]
	v_pk_fma_f32 v[56:57], v[4:5], v[120:121], v[56:57] op_sel:[0,1,0]
	v_add_co_u32_e32 v4, vcc, s24, v106
	v_pk_fma_f32 v[48:49], v[6:7], v[48:49], v[86:87] op_sel:[0,1,0]
	s_nop 0
	v_addc_co_u32_e32 v5, vcc, 0, v107, vcc
	v_pk_fma_f32 v[86:87], v[6:7], v[112:113], v[156:157] op_sel:[0,1,0]
	v_pk_fma_f32 v[68:69], v[6:7], v[78:79], v[68:69] op_sel:[0,1,0]
	v_pk_fma_f32 v[62:63], v[6:7], v[116:117], v[62:63] op_sel:[0,1,0]
	v_pk_fma_f32 v[58:59], v[6:7], v[120:121], v[58:59] op_sel:[0,1,0]
	s_mov_b32 s24, 0x2a000
	s_waitcnt vmcnt(8)
	v_mov_b64_e32 v[4:5], v[240:241]
	v_mov_b64_e32 v[6:7], v[242:243]
	v_pk_fma_f32 v[66:67], v[4:5], v[2:3], v[66:67] op_sel_hi:[1,0,1]
	v_pk_fma_f32 v[70:71], v[4:5], v[10:11], v[70:71] op_sel_hi:[1,0,1]
	v_pk_fma_f32 v[108:109], v[4:5], v[14:15], v[108:109] op_sel_hi:[1,0,1]
	v_pk_fma_f32 v[116:117], v[4:5], v[18:19], v[104:105] op_sel_hi:[1,0,1]
	v_pk_fma_f32 v[124:125], v[4:5], v[22:23], v[102:103] op_sel_hi:[1,0,1]
	v_pk_fma_f32 v[128:129], v[4:5], v[26:27], v[100:101] op_sel_hi:[1,0,1]
	v_pk_fma_f32 v[132:133], v[4:5], v[30:31], v[98:99] op_sel_hi:[1,0,1]
	v_pk_fma_f32 v[136:137], v[4:5], v[34:35], v[96:97] op_sel_hi:[1,0,1]
	v_pk_fma_f32 v[148:149], v[4:5], v[38:39], v[94:95] op_sel_hi:[1,0,1]
	v_pk_fma_f32 v[152:153], v[4:5], v[42:43], v[92:93] op_sel_hi:[1,0,1]
	v_pk_fma_f32 v[156:157], v[4:5], v[46:47], v[90:91] op_sel_hi:[1,0,1]
	v_pk_fma_f32 v[160:161], v[4:5], v[50:51], v[88:89] op_sel_hi:[1,0,1]
	v_pk_fma_f32 v[164:165], v[4:5], v[54:55], v[82:83] op_sel_hi:[1,0,1]
	v_pk_fma_f32 v[168:169], v[4:5], v[114:115], v[84:85] op_sel_hi:[1,0,1]
	v_pk_fma_f32 v[64:65], v[4:5], v[80:81], v[64:65] op_sel_hi:[1,0,1]
	v_pk_fma_f32 v[172:173], v[4:5], v[118:119], v[60:61] op_sel_hi:[1,0,1]
	v_pk_fma_f32 v[176:177], v[4:5], v[122:123], v[56:57] op_sel_hi:[1,0,1]
	v_add_co_u32_e32 v4, vcc, s24, v106
	v_pk_fma_f32 v[0:1], v[6:7], v[2:3], v[0:1] op_sel_hi:[1,0,1]
	s_nop 0
	v_addc_co_u32_e32 v5, vcc, 0, v107, vcc
	v_pk_fma_f32 v[78:79], v[6:7], v[10:11], v[8:9] op_sel_hi:[1,0,1]
	v_pk_fma_f32 v[112:113], v[6:7], v[14:15], v[12:13] op_sel_hi:[1,0,1]
	v_pk_fma_f32 v[120:121], v[6:7], v[18:19], v[16:17] op_sel_hi:[1,0,1]
	v_pk_fma_f32 v[126:127], v[6:7], v[22:23], v[20:21] op_sel_hi:[1,0,1]
	v_pk_fma_f32 v[130:131], v[6:7], v[26:27], v[24:25] op_sel_hi:[1,0,1]
	v_pk_fma_f32 v[134:135], v[6:7], v[30:31], v[28:29] op_sel_hi:[1,0,1]
	v_pk_fma_f32 v[146:147], v[6:7], v[34:35], v[32:33] op_sel_hi:[1,0,1]
	v_pk_fma_f32 v[150:151], v[6:7], v[38:39], v[36:37] op_sel_hi:[1,0,1]
	v_pk_fma_f32 v[154:155], v[6:7], v[42:43], v[40:41] op_sel_hi:[1,0,1]
	v_pk_fma_f32 v[158:159], v[6:7], v[46:47], v[44:45] op_sel_hi:[1,0,1]
	v_pk_fma_f32 v[162:163], v[6:7], v[50:51], v[48:49] op_sel_hi:[1,0,1]
	v_pk_fma_f32 v[166:167], v[6:7], v[54:55], v[52:53] op_sel_hi:[1,0,1]
	v_pk_fma_f32 v[170:171], v[6:7], v[114:115], v[86:87] op_sel_hi:[1,0,1]
	v_pk_fma_f32 v[68:69], v[6:7], v[80:81], v[68:69] op_sel_hi:[1,0,1]
	v_pk_fma_f32 v[174:175], v[6:7], v[118:119], v[62:63] op_sel_hi:[1,0,1]
	v_pk_fma_f32 v[178:179], v[6:7], v[122:123], v[58:59] op_sel_hi:[1,0,1]
	v_mov_b32_e32 v2, v3
	s_waitcnt vmcnt(8)
	v_mov_b64_e32 v[4:5], v[244:245]
	v_mov_b64_e32 v[6:7], v[246:247]
	v_pk_fma_f32 v[8:9], v[6:7], v[2:3], v[0:1] op_sel_hi:[1,0,1]
	v_mov_b32_e32 v0, v11
	v_pk_fma_f32 v[102:103], v[4:5], v[0:1], v[70:71] op_sel_hi:[1,0,1]
	v_pk_fma_f32 v[12:13], v[6:7], v[0:1], v[78:79] op_sel_hi:[1,0,1]
	v_mov_b32_e32 v0, v15
	v_pk_fma_f32 v[100:101], v[4:5], v[0:1], v[108:109] op_sel_hi:[1,0,1]
	v_pk_fma_f32 v[16:17], v[6:7], v[0:1], v[112:113] op_sel_hi:[1,0,1]
	v_mov_b32_e32 v0, v19
	v_pk_fma_f32 v[98:99], v[4:5], v[0:1], v[116:117] op_sel_hi:[1,0,1]
	v_pk_fma_f32 v[20:21], v[6:7], v[0:1], v[120:121] op_sel_hi:[1,0,1]
	v_mov_b32_e32 v0, v23
	v_pk_fma_f32 v[96:97], v[4:5], v[0:1], v[124:125] op_sel_hi:[1,0,1]
	v_pk_fma_f32 v[24:25], v[6:7], v[0:1], v[126:127] op_sel_hi:[1,0,1]
	v_mov_b32_e32 v0, v27
	v_pk_fma_f32 v[94:95], v[4:5], v[0:1], v[128:129] op_sel_hi:[1,0,1]
	v_pk_fma_f32 v[28:29], v[6:7], v[0:1], v[130:131] op_sel_hi:[1,0,1]
	v_mov_b32_e32 v0, v31
	v_pk_fma_f32 v[92:93], v[4:5], v[0:1], v[132:133] op_sel_hi:[1,0,1]
	v_pk_fma_f32 v[32:33], v[6:7], v[0:1], v[134:135] op_sel_hi:[1,0,1]
	v_mov_b32_e32 v0, v35
	v_pk_fma_f32 v[90:91], v[4:5], v[0:1], v[136:137] op_sel_hi:[1,0,1]
	v_pk_fma_f32 v[36:37], v[6:7], v[0:1], v[146:147] op_sel_hi:[1,0,1]
	v_mov_b32_e32 v0, v39
	v_pk_fma_f32 v[88:89], v[4:5], v[0:1], v[148:149] op_sel_hi:[1,0,1]
	v_pk_fma_f32 v[40:41], v[6:7], v[0:1], v[150:151] op_sel_hi:[1,0,1]
	v_mov_b32_e32 v0, v43
	v_pk_fma_f32 v[86:87], v[4:5], v[0:1], v[152:153] op_sel_hi:[1,0,1]
	v_pk_fma_f32 v[44:45], v[6:7], v[0:1], v[154:155] op_sel_hi:[1,0,1]
	v_mov_b32_e32 v0, v47
	v_pk_fma_f32 v[84:85], v[4:5], v[0:1], v[156:157] op_sel_hi:[1,0,1]
	v_pk_fma_f32 v[48:49], v[6:7], v[0:1], v[158:159] op_sel_hi:[1,0,1]
	v_mov_b32_e32 v0, v51
	v_pk_fma_f32 v[82:83], v[4:5], v[0:1], v[160:161] op_sel_hi:[1,0,1]
	v_pk_fma_f32 v[52:53], v[6:7], v[0:1], v[162:163] op_sel_hi:[1,0,1]
	v_mov_b32_e32 v0, v55
	v_pk_fma_f32 v[58:59], v[4:5], v[0:1], v[164:165] op_sel_hi:[1,0,1]
	v_pk_fma_f32 v[56:57], v[6:7], v[0:1], v[166:167] op_sel_hi:[1,0,1]
	v_mov_b32_e32 v0, v115
	v_pk_fma_f32 v[62:63], v[4:5], v[0:1], v[168:169] op_sel_hi:[1,0,1]
	v_pk_fma_f32 v[60:61], v[6:7], v[0:1], v[170:171] op_sel_hi:[1,0,1]
	v_mov_b32_e32 v0, v81
	v_pk_fma_f32 v[104:105], v[4:5], v[2:3], v[66:67] op_sel_hi:[1,0,1]
	v_pk_fma_f32 v[66:67], v[4:5], v[0:1], v[64:65] op_sel_hi:[1,0,1]
	v_pk_fma_f32 v[64:65], v[6:7], v[0:1], v[68:69] op_sel_hi:[1,0,1]
	v_mov_b32_e32 v0, v119
	v_pk_fma_f32 v[70:71], v[4:5], v[0:1], v[172:173] op_sel_hi:[1,0,1]
	v_pk_fma_f32 v[68:69], v[6:7], v[0:1], v[174:175] op_sel_hi:[1,0,1]
	v_mov_b32_e32 v0, v123
	v_pk_fma_f32 v[80:81], v[4:5], v[0:1], v[176:177] op_sel_hi:[1,0,1]
	v_pk_fma_f32 v[78:79], v[6:7], v[0:1], v[178:179] op_sel_hi:[1,0,1]
	v_lshl_add_u64 v[106:107], v[76:77], 0, s[68:69]
	v_add_co_u32_e32 v212, vcc, 0x30000, v106
	s_nop 1
	v_addc_co_u32_e32 v213, vcc, 0, v107, vcc
	global_load_dwordx4 v[216:219], v[212:213], off
	v_add_co_u32_e32 v212, vcc, 0x36000, v106
	s_nop 1
	v_addc_co_u32_e32 v213, vcc, 0, v107, vcc
	global_load_dwordx4 v[220:223], v[212:213], off
	v_add_co_u32_e32 v212, vcc, 0x3c000, v106
	s_nop 1
	v_addc_co_u32_e32 v213, vcc, 0, v107, vcc
	global_load_dwordx4 v[224:227], v[212:213], off
	v_add_co_u32_e32 v212, vcc, 0x42000, v106
	s_nop 1
	v_addc_co_u32_e32 v213, vcc, 0, v107, vcc
	global_load_dwordx4 v[228:231], v[212:213], off
	v_add_co_u32_e32 v212, vcc, 0x48000, v106
	s_nop 1
	v_addc_co_u32_e32 v213, vcc, 0, v107, vcc
	global_load_dwordx4 v[232:235], v[212:213], off
	v_add_co_u32_e32 v212, vcc, 0x4e000, v106
	s_nop 1
	v_addc_co_u32_e32 v213, vcc, 0, v107, vcc
	global_load_dwordx4 v[236:239], v[212:213], off
	v_add_co_u32_e32 v212, vcc, 0x54000, v106
	s_nop 1
	v_addc_co_u32_e32 v213, vcc, 0, v107, vcc
	global_load_dwordx4 v[240:243], v[212:213], off
	v_add_co_u32_e32 v212, vcc, 0x5a000, v106
	s_nop 1
	v_addc_co_u32_e32 v213, vcc, 0, v107, vcc
	global_load_dwordx4 v[244:247], v[212:213], off
	ds_read_b128 v[4:7], v72
	ds_read_b128 v[0:3], v72 offset:16
	s_mov_b32 s24, 0xc000
	s_add_u32 s68, s68, 0x30000
	s_addc_u32 s69, s69, 0
	s_cmp_eq_u32 s68, 0xc0000
	s_waitcnt vmcnt(8) lgkmcnt(1)
	v_mov_b64_e32 v[112:113], v[180:181]
	v_mov_b64_e32 v[114:115], v[182:183]
	v_pk_fma_f32 v[108:109], v[114:115], v[4:5], v[8:9] op_sel_hi:[1,0,1]
	ds_read_b128 v[8:11], v72 offset:2048
	v_pk_fma_f32 v[104:105], v[112:113], v[4:5], v[104:105] op_sel_hi:[1,0,1]
	s_waitcnt lgkmcnt(0)
	v_pk_fma_f32 v[116:117], v[114:115], v[8:9], v[12:13] op_sel_hi:[1,0,1]
	ds_read_b128 v[12:15], v72 offset:4096
	v_pk_fma_f32 v[102:103], v[112:113], v[8:9], v[102:103] op_sel_hi:[1,0,1]
	s_waitcnt lgkmcnt(0)
	v_pk_fma_f32 v[118:119], v[114:115], v[12:13], v[16:17] op_sel_hi:[1,0,1]
	ds_read_b128 v[16:19], v72 offset:6144
	v_pk_fma_f32 v[100:101], v[112:113], v[12:13], v[100:101] op_sel_hi:[1,0,1]
	s_waitcnt lgkmcnt(0)
	v_pk_fma_f32 v[120:121], v[114:115], v[16:17], v[20:21] op_sel_hi:[1,0,1]
	ds_read_b128 v[20:23], v72 offset:8192
	v_pk_fma_f32 v[98:99], v[112:113], v[16:17], v[98:99] op_sel_hi:[1,0,1]
	s_waitcnt lgkmcnt(0)
	v_pk_fma_f32 v[122:123], v[114:115], v[20:21], v[24:25] op_sel_hi:[1,0,1]
	ds_read_b128 v[24:27], v72 offset:10240
	v_pk_fma_f32 v[96:97], v[112:113], v[20:21], v[96:97] op_sel_hi:[1,0,1]
	s_waitcnt lgkmcnt(0)
	v_pk_fma_f32 v[124:125], v[114:115], v[24:25], v[28:29] op_sel_hi:[1,0,1]
	ds_read_b128 v[28:31], v72 offset:12288
	v_pk_fma_f32 v[94:95], v[112:113], v[24:25], v[94:95] op_sel_hi:[1,0,1]
	s_waitcnt lgkmcnt(0)
	v_pk_fma_f32 v[126:127], v[114:115], v[28:29], v[32:33] op_sel_hi:[1,0,1]
	ds_read_b128 v[32:35], v72 offset:14336
	v_pk_fma_f32 v[92:93], v[112:113], v[28:29], v[92:93] op_sel_hi:[1,0,1]
	s_waitcnt lgkmcnt(0)
	v_pk_fma_f32 v[128:129], v[114:115], v[32:33], v[36:37] op_sel_hi:[1,0,1]
	ds_read_b128 v[36:39], v72 offset:16384
	v_pk_fma_f32 v[90:91], v[112:113], v[32:33], v[90:91] op_sel_hi:[1,0,1]
	s_waitcnt lgkmcnt(0)
	v_pk_fma_f32 v[130:131], v[114:115], v[36:37], v[40:41] op_sel_hi:[1,0,1]
	ds_read_b128 v[40:43], v72 offset:18432
	v_pk_fma_f32 v[88:89], v[112:113], v[36:37], v[88:89] op_sel_hi:[1,0,1]
	s_waitcnt lgkmcnt(0)
	v_pk_fma_f32 v[132:133], v[114:115], v[40:41], v[44:45] op_sel_hi:[1,0,1]
	ds_read_b128 v[44:47], v72 offset:20480
	v_pk_fma_f32 v[86:87], v[112:113], v[40:41], v[86:87] op_sel_hi:[1,0,1]
	s_waitcnt lgkmcnt(0)
	v_pk_fma_f32 v[134:135], v[114:115], v[44:45], v[48:49] op_sel_hi:[1,0,1]
	ds_read_b128 v[48:51], v72 offset:22528
	v_pk_fma_f32 v[84:85], v[112:113], v[44:45], v[84:85] op_sel_hi:[1,0,1]
	s_waitcnt lgkmcnt(0)
	v_pk_fma_f32 v[136:137], v[114:115], v[48:49], v[52:53] op_sel_hi:[1,0,1]
	ds_read_b128 v[52:55], v72 offset:24576
	v_pk_fma_f32 v[82:83], v[112:113], v[48:49], v[82:83] op_sel_hi:[1,0,1]
	s_waitcnt lgkmcnt(0)
	v_pk_fma_f32 v[146:147], v[112:113], v[52:53], v[58:59] op_sel_hi:[1,0,1]
	v_pk_fma_f32 v[148:149], v[114:115], v[52:53], v[56:57] op_sel_hi:[1,0,1]
	ds_read_b128 v[56:59], v72 offset:26624
	s_waitcnt lgkmcnt(0)
	v_pk_fma_f32 v[150:151], v[112:113], v[56:57], v[62:63] op_sel_hi:[1,0,1]
	v_pk_fma_f32 v[152:153], v[114:115], v[56:57], v[60:61] op_sel_hi:[1,0,1]
	ds_read_b128 v[60:63], v72 offset:28672
	s_waitcnt lgkmcnt(0)
	v_pk_fma_f32 v[154:155], v[112:113], v[60:61], v[66:67] op_sel_hi:[1,0,1]
	v_pk_fma_f32 v[156:157], v[114:115], v[60:61], v[64:65] op_sel_hi:[1,0,1]
	ds_read_b128 v[64:67], v72 offset:30720
	s_waitcnt lgkmcnt(0)
	v_pk_fma_f32 v[158:159], v[112:113], v[64:65], v[70:71] op_sel_hi:[1,0,1]
	v_pk_fma_f32 v[160:161], v[114:115], v[64:65], v[68:69] op_sel_hi:[1,0,1]
	ds_read_b128 v[68:71], v72 offset:32768
	s_waitcnt lgkmcnt(0)
	v_pk_fma_f32 v[114:115], v[114:115], v[68:69], v[78:79] op_sel_hi:[1,0,1]
	v_add_co_u32_e32 v78, vcc, s75, v106
	v_pk_fma_f32 v[112:113], v[112:113], v[68:69], v[80:81] op_sel_hi:[1,0,1]
	s_nop 0
	v_addc_co_u32_e32 v79, vcc, 0, v107, vcc
	s_waitcnt vmcnt(8)
	v_mov_b64_e32 v[78:79], v[184:185]
	v_mov_b64_e32 v[80:81], v[186:187]
	v_pk_fma_f32 v[104:105], v[78:79], v[4:5], v[104:105] op_sel:[0,1,0]
	v_pk_fma_f32 v[4:5], v[80:81], v[4:5], v[108:109] op_sel:[0,1,0]
	v_pk_fma_f32 v[102:103], v[78:79], v[8:9], v[102:103] op_sel:[0,1,0]
	v_pk_fma_f32 v[8:9], v[80:81], v[8:9], v[116:117] op_sel:[0,1,0]
	v_pk_fma_f32 v[100:101], v[78:79], v[12:13], v[100:101] op_sel:[0,1,0]
	v_pk_fma_f32 v[12:13], v[80:81], v[12:13], v[118:119] op_sel:[0,1,0]
	v_pk_fma_f32 v[98:99], v[78:79], v[16:17], v[98:99] op_sel:[0,1,0]
	v_pk_fma_f32 v[16:17], v[80:81], v[16:17], v[120:121] op_sel:[0,1,0]
	v_pk_fma_f32 v[96:97], v[78:79], v[20:21], v[96:97] op_sel:[0,1,0]
	v_pk_fma_f32 v[94:95], v[78:79], v[24:25], v[94:95] op_sel:[0,1,0]
	v_pk_fma_f32 v[92:93], v[78:79], v[28:29], v[92:93] op_sel:[0,1,0]
	v_pk_fma_f32 v[90:91], v[78:79], v[32:33], v[90:91] op_sel:[0,1,0]
	v_pk_fma_f32 v[88:89], v[78:79], v[36:37], v[88:89] op_sel:[0,1,0]
	v_pk_fma_f32 v[86:87], v[78:79], v[40:41], v[86:87] op_sel:[0,1,0]
	v_pk_fma_f32 v[84:85], v[78:79], v[44:45], v[84:85] op_sel:[0,1,0]
	v_pk_fma_f32 v[82:83], v[78:79], v[48:49], v[82:83] op_sel:[0,1,0]
	v_pk_fma_f32 v[108:109], v[78:79], v[52:53], v[146:147] op_sel:[0,1,0]
	v_pk_fma_f32 v[116:117], v[78:79], v[56:57], v[150:151] op_sel:[0,1,0]
	v_pk_fma_f32 v[118:119], v[78:79], v[60:61], v[154:155] op_sel:[0,1,0]
	v_pk_fma_f32 v[120:121], v[78:79], v[64:65], v[158:159] op_sel:[0,1,0]
	v_pk_fma_f32 v[112:113], v[78:79], v[68:69], v[112:113] op_sel:[0,1,0]
	v_add_co_u32_e32 v78, vcc, s24, v106
	v_pk_fma_f32 v[20:21], v[80:81], v[20:21], v[122:123] op_sel:[0,1,0]
	s_nop 0
	v_addc_co_u32_e32 v79, vcc, 0, v107, vcc
	v_pk_fma_f32 v[24:25], v[80:81], v[24:25], v[124:125] op_sel:[0,1,0]
	v_pk_fma_f32 v[28:29], v[80:81], v[28:29], v[126:127] op_sel:[0,1,0]
	v_pk_fma_f32 v[32:33], v[80:81], v[32:33], v[128:129] op_sel:[0,1,0]
	v_pk_fma_f32 v[36:37], v[80:81], v[36:37], v[130:131] op_sel:[0,1,0]
	v_pk_fma_f32 v[40:41], v[80:81], v[40:41], v[132:133] op_sel:[0,1,0]
	v_pk_fma_f32 v[44:45], v[80:81], v[44:45], v[134:135] op_sel:[0,1,0]
	v_pk_fma_f32 v[48:49], v[80:81], v[48:49], v[136:137] op_sel:[0,1,0]
	v_pk_fma_f32 v[52:53], v[80:81], v[52:53], v[148:149] op_sel:[0,1,0]
	v_pk_fma_f32 v[56:57], v[80:81], v[56:57], v[152:153] op_sel:[0,1,0]
	v_pk_fma_f32 v[60:61], v[80:81], v[60:61], v[156:157] op_sel:[0,1,0]
	v_pk_fma_f32 v[64:65], v[80:81], v[64:65], v[160:161] op_sel:[0,1,0]
	v_pk_fma_f32 v[68:69], v[80:81], v[68:69], v[114:115] op_sel:[0,1,0]
	s_mov_b32 s24, 0x12000
	s_waitcnt vmcnt(8)
	v_mov_b64_e32 v[78:79], v[188:189]
	v_mov_b64_e32 v[80:81], v[190:191]
	v_pk_fma_f32 v[122:123], v[80:81], v[14:15], v[12:13] op_sel_hi:[1,0,1]
	v_add_co_u32_e32 v12, vcc, s24, v106
	v_pk_fma_f32 v[156:157], v[78:79], v[70:71], v[112:113] op_sel_hi:[1,0,1]
	s_nop 0
	v_addc_co_u32_e32 v13, vcc, 0, v107, vcc
	v_pk_fma_f32 v[104:105], v[78:79], v[6:7], v[104:105] op_sel_hi:[1,0,1]
	v_pk_fma_f32 v[4:5], v[80:81], v[6:7], v[4:5] op_sel_hi:[1,0,1]
	v_mov_b32_e32 v6, v7
	v_pk_fma_f32 v[102:103], v[78:79], v[10:11], v[102:103] op_sel_hi:[1,0,1]
	v_pk_fma_f32 v[8:9], v[80:81], v[10:11], v[8:9] op_sel_hi:[1,0,1]
	v_pk_fma_f32 v[100:101], v[78:79], v[14:15], v[100:101] op_sel_hi:[1,0,1]
	v_pk_fma_f32 v[150:151], v[78:79], v[54:55], v[108:109] op_sel_hi:[1,0,1]
	v_pk_fma_f32 v[98:99], v[78:79], v[18:19], v[98:99] op_sel_hi:[1,0,1]
	v_pk_fma_f32 v[124:125], v[80:81], v[18:19], v[16:17] op_sel_hi:[1,0,1]
	v_pk_fma_f32 v[96:97], v[78:79], v[22:23], v[96:97] op_sel_hi:[1,0,1]
	v_pk_fma_f32 v[126:127], v[80:81], v[22:23], v[20:21] op_sel_hi:[1,0,1]
	v_pk_fma_f32 v[94:95], v[78:79], v[26:27], v[94:95] op_sel_hi:[1,0,1]
	v_pk_fma_f32 v[128:129], v[80:81], v[26:27], v[24:25] op_sel_hi:[1,0,1]
	v_pk_fma_f32 v[92:93], v[78:79], v[30:31], v[92:93] op_sel_hi:[1,0,1]
	v_pk_fma_f32 v[130:131], v[80:81], v[30:31], v[28:29] op_sel_hi:[1,0,1]
	v_pk_fma_f32 v[90:91], v[78:79], v[34:35], v[90:91] op_sel_hi:[1,0,1]
	v_pk_fma_f32 v[132:133], v[80:81], v[34:35], v[32:33] op_sel_hi:[1,0,1]
	v_pk_fma_f32 v[88:89], v[78:79], v[38:39], v[88:89] op_sel_hi:[1,0,1]
	v_pk_fma_f32 v[134:135], v[80:81], v[38:39], v[36:37] op_sel_hi:[1,0,1]
	v_pk_fma_f32 v[86:87], v[78:79], v[42:43], v[86:87] op_sel_hi:[1,0,1]
	v_pk_fma_f32 v[136:137], v[80:81], v[42:43], v[40:41] op_sel_hi:[1,0,1]
	v_pk_fma_f32 v[84:85], v[78:79], v[46:47], v[84:85] op_sel_hi:[1,0,1]
	v_pk_fma_f32 v[146:147], v[80:81], v[46:47], v[44:45] op_sel_hi:[1,0,1]
	v_pk_fma_f32 v[82:83], v[78:79], v[50:51], v[82:83] op_sel_hi:[1,0,1]
	v_pk_fma_f32 v[148:149], v[80:81], v[50:51], v[48:49] op_sel_hi:[1,0,1]
	v_pk_fma_f32 v[152:153], v[80:81], v[54:55], v[52:53] op_sel_hi:[1,0,1]
	v_pk_fma_f32 v[116:117], v[78:79], v[58:59], v[116:117] op_sel_hi:[1,0,1]
	v_pk_fma_f32 v[56:57], v[80:81], v[58:59], v[56:57] op_sel_hi:[1,0,1]
	v_pk_fma_f32 v[118:119], v[78:79], v[62:63], v[118:119] op_sel_hi:[1,0,1]
	v_pk_fma_f32 v[60:61], v[80:81], v[62:63], v[60:61] op_sel_hi:[1,0,1]
	v_pk_fma_f32 v[120:121], v[78:79], v[66:67], v[120:121] op_sel_hi:[1,0,1]
	v_pk_fma_f32 v[154:155], v[80:81], v[66:67], v[64:65] op_sel_hi:[1,0,1]
	v_pk_fma_f32 v[158:159], v[80:81], v[70:71], v[68:69] op_sel_hi:[1,0,1]
	s_mov_b32 s24, 0x18000
	s_waitcnt vmcnt(8)
	v_mov_b64_e32 v[112:113], v[192:193]
	v_mov_b64_e32 v[114:115], v[194:195]
	v_pk_fma_f32 v[162:163], v[114:115], v[6:7], v[4:5] op_sel_hi:[1,0,1]
	v_mov_b32_e32 v4, v11
	v_pk_fma_f32 v[12:13], v[112:113], v[4:5], v[102:103] op_sel_hi:[1,0,1]
	v_pk_fma_f32 v[108:109], v[114:115], v[4:5], v[8:9] op_sel_hi:[1,0,1]
	v_mov_b32_e32 v4, v15
	v_pk_fma_f32 v[160:161], v[112:113], v[6:7], v[104:105] op_sel_hi:[1,0,1]
	v_pk_fma_f32 v[16:17], v[112:113], v[4:5], v[100:101] op_sel_hi:[1,0,1]
	v_pk_fma_f32 v[104:105], v[114:115], v[4:5], v[122:123] op_sel_hi:[1,0,1]
	v_mov_b32_e32 v4, v19
	v_pk_fma_f32 v[20:21], v[112:113], v[4:5], v[98:99] op_sel_hi:[1,0,1]
	v_pk_fma_f32 v[102:103], v[114:115], v[4:5], v[124:125] op_sel_hi:[1,0,1]
	v_mov_b32_e32 v4, v23
	v_pk_fma_f32 v[24:25], v[112:113], v[4:5], v[96:97] op_sel_hi:[1,0,1]
	v_pk_fma_f32 v[100:101], v[114:115], v[4:5], v[126:127] op_sel_hi:[1,0,1]
	v_mov_b32_e32 v4, v27
	v_pk_fma_f32 v[28:29], v[112:113], v[4:5], v[94:95] op_sel_hi:[1,0,1]
	v_pk_fma_f32 v[98:99], v[114:115], v[4:5], v[128:129] op_sel_hi:[1,0,1]
	v_mov_b32_e32 v4, v31
	v_pk_fma_f32 v[32:33], v[112:113], v[4:5], v[92:93] op_sel_hi:[1,0,1]
	v_pk_fma_f32 v[96:97], v[114:115], v[4:5], v[130:131] op_sel_hi:[1,0,1]
	v_mov_b32_e32 v4, v35
	v_pk_fma_f32 v[36:37], v[112:113], v[4:5], v[90:91] op_sel_hi:[1,0,1]
	v_pk_fma_f32 v[94:95], v[114:115], v[4:5], v[132:133] op_sel_hi:[1,0,1]
	v_mov_b32_e32 v4, v39
	v_pk_fma_f32 v[40:41], v[112:113], v[4:5], v[88:89] op_sel_hi:[1,0,1]
	v_pk_fma_f32 v[92:93], v[114:115], v[4:5], v[134:135] op_sel_hi:[1,0,1]
	v_mov_b32_e32 v4, v43
	v_pk_fma_f32 v[44:45], v[112:113], v[4:5], v[86:87] op_sel_hi:[1,0,1]
	v_pk_fma_f32 v[90:91], v[114:115], v[4:5], v[136:137] op_sel_hi:[1,0,1]
	v_mov_b32_e32 v4, v47
	v_pk_fma_f32 v[48:49], v[112:113], v[4:5], v[84:85] op_sel_hi:[1,0,1]
	v_pk_fma_f32 v[88:89], v[114:115], v[4:5], v[146:147] op_sel_hi:[1,0,1]
	v_mov_b32_e32 v4, v51
	v_pk_fma_f32 v[52:53], v[112:113], v[4:5], v[82:83] op_sel_hi:[1,0,1]
	v_pk_fma_f32 v[86:87], v[114:115], v[4:5], v[148:149] op_sel_hi:[1,0,1]
	v_mov_b32_e32 v4, v55
	v_pk_fma_f32 v[82:83], v[112:113], v[4:5], v[150:151] op_sel_hi:[1,0,1]
	v_pk_fma_f32 v[84:85], v[114:115], v[4:5], v[152:153] op_sel_hi:[1,0,1]
	v_mov_b32_e32 v4, v59
	v_pk_fma_f32 v[78:79], v[112:113], v[4:5], v[116:117] op_sel_hi:[1,0,1]
	v_pk_fma_f32 v[80:81], v[114:115], v[4:5], v[56:57] op_sel_hi:[1,0,1]
	v_mov_b32_e32 v4, v63
	v_pk_fma_f32 v[64:65], v[112:113], v[4:5], v[118:119] op_sel_hi:[1,0,1]
	v_pk_fma_f32 v[68:69], v[114:115], v[4:5], v[60:61] op_sel_hi:[1,0,1]
	v_mov_b32_e32 v4, v67
	v_pk_fma_f32 v[60:61], v[112:113], v[4:5], v[120:121] op_sel_hi:[1,0,1]
	v_pk_fma_f32 v[62:63], v[114:115], v[4:5], v[154:155] op_sel_hi:[1,0,1]
	v_mov_b32_e32 v4, v71
	v_pk_fma_f32 v[56:57], v[112:113], v[4:5], v[156:157] op_sel_hi:[1,0,1]
	v_pk_fma_f32 v[58:59], v[114:115], v[4:5], v[158:159] op_sel_hi:[1,0,1]
	v_add_co_u32_e32 v4, vcc, s24, v106
	ds_read_b128 v[8:11], v72 offset:2064
	ds_read_b128 v[120:123], v72 offset:32784
	v_addc_co_u32_e32 v5, vcc, 0, v107, vcc
	ds_read_b128 v[112:115], v72 offset:26640
	ds_read_b128 v[116:119], v72 offset:30736
	s_mov_b32 s24, 0x1e000
	s_waitcnt vmcnt(8) lgkmcnt(3)
	v_mov_b64_e32 v[4:5], v[196:197]
	v_mov_b64_e32 v[6:7], v[198:199]
	v_pk_fma_f32 v[124:125], v[4:5], v[8:9], v[12:13] op_sel_hi:[1,0,1]
	ds_read_b128 v[12:15], v72 offset:4112
	s_waitcnt lgkmcnt(2)
	v_pk_fma_f32 v[154:155], v[4:5], v[112:113], v[78:79] op_sel_hi:[1,0,1]
	v_pk_fma_f32 v[156:157], v[6:7], v[112:113], v[80:81] op_sel_hi:[1,0,1]
	ds_read_b128 v[78:81], v72 offset:28688
	v_pk_fma_f32 v[66:67], v[4:5], v[0:1], v[160:161] op_sel_hi:[1,0,1]
	s_waitcnt lgkmcnt(1)
	v_pk_fma_f32 v[126:127], v[4:5], v[12:13], v[16:17] op_sel_hi:[1,0,1]
	ds_read_b128 v[16:19], v72 offset:6160
	v_pk_fma_f32 v[60:61], v[4:5], v[116:117], v[60:61] op_sel_hi:[1,0,1]
	s_waitcnt lgkmcnt(1)
	v_pk_fma_f32 v[64:65], v[4:5], v[78:79], v[64:65] op_sel_hi:[1,0,1]
	v_pk_fma_f32 v[56:57], v[4:5], v[120:121], v[56:57] op_sel_hi:[1,0,1]
	v_pk_fma_f32 v[70:71], v[6:7], v[0:1], v[162:163] op_sel_hi:[1,0,1]
	s_waitcnt lgkmcnt(0)
	v_pk_fma_f32 v[128:129], v[4:5], v[16:17], v[20:21] op_sel_hi:[1,0,1]
	ds_read_b128 v[20:23], v72 offset:8208
	v_pk_fma_f32 v[108:109], v[6:7], v[8:9], v[108:109] op_sel_hi:[1,0,1]
	v_pk_fma_f32 v[104:105], v[6:7], v[12:13], v[104:105] op_sel_hi:[1,0,1]
	v_pk_fma_f32 v[102:103], v[6:7], v[16:17], v[102:103] op_sel_hi:[1,0,1]
	v_pk_fma_f32 v[68:69], v[6:7], v[78:79], v[68:69] op_sel_hi:[1,0,1]
	s_waitcnt lgkmcnt(0)
	v_pk_fma_f32 v[130:131], v[4:5], v[20:21], v[24:25] op_sel_hi:[1,0,1]
	ds_read_b128 v[24:27], v72 offset:10256
	v_pk_fma_f32 v[100:101], v[6:7], v[20:21], v[100:101] op_sel_hi:[1,0,1]
	v_pk_fma_f32 v[62:63], v[6:7], v[116:117], v[62:63] op_sel_hi:[1,0,1]
	v_pk_fma_f32 v[58:59], v[6:7], v[120:121], v[58:59] op_sel_hi:[1,0,1]
	s_waitcnt lgkmcnt(0)
	v_pk_fma_f32 v[132:133], v[4:5], v[24:25], v[28:29] op_sel_hi:[1,0,1]
	ds_read_b128 v[28:31], v72 offset:12304
	v_pk_fma_f32 v[98:99], v[6:7], v[24:25], v[98:99] op_sel_hi:[1,0,1]
	s_waitcnt lgkmcnt(0)
	v_pk_fma_f32 v[134:135], v[4:5], v[28:29], v[32:33] op_sel_hi:[1,0,1]
	ds_read_b128 v[32:35], v72 offset:14352
	v_pk_fma_f32 v[96:97], v[6:7], v[28:29], v[96:97] op_sel_hi:[1,0,1]
	s_waitcnt lgkmcnt(0)
	v_pk_fma_f32 v[136:137], v[4:5], v[32:33], v[36:37] op_sel_hi:[1,0,1]
	ds_read_b128 v[36:39], v72 offset:16400
	v_pk_fma_f32 v[94:95], v[6:7], v[32:33], v[94:95] op_sel_hi:[1,0,1]
	s_waitcnt lgkmcnt(0)
	v_pk_fma_f32 v[146:147], v[4:5], v[36:37], v[40:41] op_sel_hi:[1,0,1]
	ds_read_b128 v[40:43], v72 offset:18448
	v_pk_fma_f32 v[92:93], v[6:7], v[36:37], v[92:93] op_sel_hi:[1,0,1]
	s_waitcnt lgkmcnt(0)
	v_pk_fma_f32 v[148:149], v[4:5], v[40:41], v[44:45] op_sel_hi:[1,0,1]
	ds_read_b128 v[44:47], v72 offset:20496
	v_pk_fma_f32 v[90:91], v[6:7], v[40:41], v[90:91] op_sel_hi:[1,0,1]
	s_waitcnt lgkmcnt(0)
	v_pk_fma_f32 v[150:151], v[4:5], v[44:45], v[48:49] op_sel_hi:[1,0,1]
	ds_read_b128 v[48:51], v72 offset:22544
	v_pk_fma_f32 v[88:89], v[6:7], v[44:45], v[88:89] op_sel_hi:[1,0,1]
	s_waitcnt lgkmcnt(0)
	v_pk_fma_f32 v[152:153], v[4:5], v[48:49], v[52:53] op_sel_hi:[1,0,1]
	ds_read_b128 v[52:55], v72 offset:24592
	v_pk_fma_f32 v[86:87], v[6:7], v[48:49], v[86:87] op_sel_hi:[1,0,1]
	v_add_u32_e32 v72, 32, v72
	s_waitcnt lgkmcnt(0)
	v_pk_fma_f32 v[82:83], v[4:5], v[52:53], v[82:83] op_sel_hi:[1,0,1]
	v_add_co_u32_e32 v4, vcc, s24, v106
	v_pk_fma_f32 v[84:85], v[6:7], v[52:53], v[84:85] op_sel_hi:[1,0,1]
	s_nop 0
	v_addc_co_u32_e32 v5, vcc, 0, v107, vcc
	s_mov_b32 s24, 0x24000
	s_waitcnt vmcnt(8)
	v_mov_b64_e32 v[4:5], v[200:201]
	v_mov_b64_e32 v[6:7], v[202:203]
	v_pk_fma_f32 v[66:67], v[4:5], v[0:1], v[66:67] op_sel:[0,1,0]
	v_pk_fma_f32 v[0:1], v[6:7], v[0:1], v[70:71] op_sel:[0,1,0]
	v_pk_fma_f32 v[70:71], v[4:5], v[8:9], v[124:125] op_sel:[0,1,0]
	v_pk_fma_f32 v[8:9], v[6:7], v[8:9], v[108:109] op_sel:[0,1,0]
	v_pk_fma_f32 v[108:109], v[4:5], v[12:13], v[126:127] op_sel:[0,1,0]
	v_pk_fma_f32 v[12:13], v[6:7], v[12:13], v[104:105] op_sel:[0,1,0]
	v_pk_fma_f32 v[104:105], v[4:5], v[16:17], v[128:129] op_sel:[0,1,0]
	v_pk_fma_f32 v[16:17], v[6:7], v[16:17], v[102:103] op_sel:[0,1,0]
	v_pk_fma_f32 v[102:103], v[4:5], v[20:21], v[130:131] op_sel:[0,1,0]
	v_pk_fma_f32 v[20:21], v[6:7], v[20:21], v[100:101] op_sel:[0,1,0]
	v_pk_fma_f32 v[100:101], v[4:5], v[24:25], v[132:133] op_sel:[0,1,0]
	v_pk_fma_f32 v[24:25], v[6:7], v[24:25], v[98:99] op_sel:[0,1,0]
	v_pk_fma_f32 v[98:99], v[4:5], v[28:29], v[134:135] op_sel:[0,1,0]
	v_pk_fma_f32 v[28:29], v[6:7], v[28:29], v[96:97] op_sel:[0,1,0]
	v_pk_fma_f32 v[96:97], v[4:5], v[32:33], v[136:137] op_sel:[0,1,0]
	v_pk_fma_f32 v[32:33], v[6:7], v[32:33], v[94:95] op_sel:[0,1,0]
	v_pk_fma_f32 v[94:95], v[4:5], v[36:37], v[146:147] op_sel:[0,1,0]
	v_pk_fma_f32 v[36:37], v[6:7], v[36:37], v[92:93] op_sel:[0,1,0]
	v_pk_fma_f32 v[92:93], v[4:5], v[40:41], v[148:149] op_sel:[0,1,0]
	v_pk_fma_f32 v[40:41], v[6:7], v[40:41], v[90:91] op_sel:[0,1,0]
	v_pk_fma_f32 v[90:91], v[4:5], v[44:45], v[150:151] op_sel:[0,1,0]
	v_pk_fma_f32 v[44:45], v[6:7], v[44:45], v[88:89] op_sel:[0,1,0]
	v_pk_fma_f32 v[88:89], v[4:5], v[48:49], v[152:153] op_sel:[0,1,0]
	v_pk_fma_f32 v[82:83], v[4:5], v[52:53], v[82:83] op_sel:[0,1,0]
	v_pk_fma_f32 v[52:53], v[6:7], v[52:53], v[84:85] op_sel:[0,1,0]
	v_pk_fma_f32 v[84:85], v[4:5], v[112:113], v[154:155] op_sel:[0,1,0]
	v_pk_fma_f32 v[64:65], v[4:5], v[78:79], v[64:65] op_sel:[0,1,0]
	v_pk_fma_f32 v[60:61], v[4:5], v[116:117], v[60:61] op_sel:[0,1,0]
	v_pk_fma_f32 v[56:57], v[4:5], v[120:121], v[56:57] op_sel:[0,1,0]
	v_add_co_u32_e32 v4, vcc, s24, v106
	v_pk_fma_f32 v[48:49], v[6:7], v[48:49], v[86:87] op_sel:[0,1,0]
	s_nop 0
	v_addc_co_u32_e32 v5, vcc, 0, v107, vcc
	v_pk_fma_f32 v[86:87], v[6:7], v[112:113], v[156:157] op_sel:[0,1,0]
	v_pk_fma_f32 v[68:69], v[6:7], v[78:79], v[68:69] op_sel:[0,1,0]
	v_pk_fma_f32 v[62:63], v[6:7], v[116:117], v[62:63] op_sel:[0,1,0]
	v_pk_fma_f32 v[58:59], v[6:7], v[120:121], v[58:59] op_sel:[0,1,0]
	s_mov_b32 s24, 0x2a000
	s_waitcnt vmcnt(8)
	v_mov_b64_e32 v[4:5], v[204:205]
	v_mov_b64_e32 v[6:7], v[206:207]
	v_pk_fma_f32 v[66:67], v[4:5], v[2:3], v[66:67] op_sel_hi:[1,0,1]
	v_pk_fma_f32 v[70:71], v[4:5], v[10:11], v[70:71] op_sel_hi:[1,0,1]
	v_pk_fma_f32 v[108:109], v[4:5], v[14:15], v[108:109] op_sel_hi:[1,0,1]
	v_pk_fma_f32 v[116:117], v[4:5], v[18:19], v[104:105] op_sel_hi:[1,0,1]
	v_pk_fma_f32 v[124:125], v[4:5], v[22:23], v[102:103] op_sel_hi:[1,0,1]
	v_pk_fma_f32 v[128:129], v[4:5], v[26:27], v[100:101] op_sel_hi:[1,0,1]
	v_pk_fma_f32 v[132:133], v[4:5], v[30:31], v[98:99] op_sel_hi:[1,0,1]
	v_pk_fma_f32 v[136:137], v[4:5], v[34:35], v[96:97] op_sel_hi:[1,0,1]
	v_pk_fma_f32 v[148:149], v[4:5], v[38:39], v[94:95] op_sel_hi:[1,0,1]
	v_pk_fma_f32 v[152:153], v[4:5], v[42:43], v[92:93] op_sel_hi:[1,0,1]
	v_pk_fma_f32 v[156:157], v[4:5], v[46:47], v[90:91] op_sel_hi:[1,0,1]
	v_pk_fma_f32 v[160:161], v[4:5], v[50:51], v[88:89] op_sel_hi:[1,0,1]
	v_pk_fma_f32 v[164:165], v[4:5], v[54:55], v[82:83] op_sel_hi:[1,0,1]
	v_pk_fma_f32 v[168:169], v[4:5], v[114:115], v[84:85] op_sel_hi:[1,0,1]
	v_pk_fma_f32 v[64:65], v[4:5], v[80:81], v[64:65] op_sel_hi:[1,0,1]
	v_pk_fma_f32 v[172:173], v[4:5], v[118:119], v[60:61] op_sel_hi:[1,0,1]
	v_pk_fma_f32 v[176:177], v[4:5], v[122:123], v[56:57] op_sel_hi:[1,0,1]
	v_add_co_u32_e32 v4, vcc, s24, v106
	v_pk_fma_f32 v[0:1], v[6:7], v[2:3], v[0:1] op_sel_hi:[1,0,1]
	s_nop 0
	v_addc_co_u32_e32 v5, vcc, 0, v107, vcc
	v_pk_fma_f32 v[78:79], v[6:7], v[10:11], v[8:9] op_sel_hi:[1,0,1]
	v_pk_fma_f32 v[112:113], v[6:7], v[14:15], v[12:13] op_sel_hi:[1,0,1]
	v_pk_fma_f32 v[120:121], v[6:7], v[18:19], v[16:17] op_sel_hi:[1,0,1]
	v_pk_fma_f32 v[126:127], v[6:7], v[22:23], v[20:21] op_sel_hi:[1,0,1]
	v_pk_fma_f32 v[130:131], v[6:7], v[26:27], v[24:25] op_sel_hi:[1,0,1]
	v_pk_fma_f32 v[134:135], v[6:7], v[30:31], v[28:29] op_sel_hi:[1,0,1]
	v_pk_fma_f32 v[146:147], v[6:7], v[34:35], v[32:33] op_sel_hi:[1,0,1]
	v_pk_fma_f32 v[150:151], v[6:7], v[38:39], v[36:37] op_sel_hi:[1,0,1]
	v_pk_fma_f32 v[154:155], v[6:7], v[42:43], v[40:41] op_sel_hi:[1,0,1]
	v_pk_fma_f32 v[158:159], v[6:7], v[46:47], v[44:45] op_sel_hi:[1,0,1]
	v_pk_fma_f32 v[162:163], v[6:7], v[50:51], v[48:49] op_sel_hi:[1,0,1]
	v_pk_fma_f32 v[166:167], v[6:7], v[54:55], v[52:53] op_sel_hi:[1,0,1]
	v_pk_fma_f32 v[170:171], v[6:7], v[114:115], v[86:87] op_sel_hi:[1,0,1]
	v_pk_fma_f32 v[68:69], v[6:7], v[80:81], v[68:69] op_sel_hi:[1,0,1]
	v_pk_fma_f32 v[174:175], v[6:7], v[118:119], v[62:63] op_sel_hi:[1,0,1]
	v_pk_fma_f32 v[178:179], v[6:7], v[122:123], v[58:59] op_sel_hi:[1,0,1]
	v_mov_b32_e32 v2, v3
	s_waitcnt vmcnt(8)
	v_mov_b64_e32 v[4:5], v[208:209]
	v_mov_b64_e32 v[6:7], v[210:211]
	v_pk_fma_f32 v[8:9], v[6:7], v[2:3], v[0:1] op_sel_hi:[1,0,1]
	v_mov_b32_e32 v0, v11
	v_pk_fma_f32 v[102:103], v[4:5], v[0:1], v[70:71] op_sel_hi:[1,0,1]
	v_pk_fma_f32 v[12:13], v[6:7], v[0:1], v[78:79] op_sel_hi:[1,0,1]
	v_mov_b32_e32 v0, v15
	v_pk_fma_f32 v[100:101], v[4:5], v[0:1], v[108:109] op_sel_hi:[1,0,1]
	v_pk_fma_f32 v[16:17], v[6:7], v[0:1], v[112:113] op_sel_hi:[1,0,1]
	v_mov_b32_e32 v0, v19
	v_pk_fma_f32 v[98:99], v[4:5], v[0:1], v[116:117] op_sel_hi:[1,0,1]
	v_pk_fma_f32 v[20:21], v[6:7], v[0:1], v[120:121] op_sel_hi:[1,0,1]
	v_mov_b32_e32 v0, v23
	v_pk_fma_f32 v[96:97], v[4:5], v[0:1], v[124:125] op_sel_hi:[1,0,1]
	v_pk_fma_f32 v[24:25], v[6:7], v[0:1], v[126:127] op_sel_hi:[1,0,1]
	v_mov_b32_e32 v0, v27
	v_pk_fma_f32 v[94:95], v[4:5], v[0:1], v[128:129] op_sel_hi:[1,0,1]
	v_pk_fma_f32 v[28:29], v[6:7], v[0:1], v[130:131] op_sel_hi:[1,0,1]
	v_mov_b32_e32 v0, v31
	v_pk_fma_f32 v[92:93], v[4:5], v[0:1], v[132:133] op_sel_hi:[1,0,1]
	v_pk_fma_f32 v[32:33], v[6:7], v[0:1], v[134:135] op_sel_hi:[1,0,1]
	v_mov_b32_e32 v0, v35
	v_pk_fma_f32 v[90:91], v[4:5], v[0:1], v[136:137] op_sel_hi:[1,0,1]
	v_pk_fma_f32 v[36:37], v[6:7], v[0:1], v[146:147] op_sel_hi:[1,0,1]
	v_mov_b32_e32 v0, v39
	v_pk_fma_f32 v[88:89], v[4:5], v[0:1], v[148:149] op_sel_hi:[1,0,1]
	v_pk_fma_f32 v[40:41], v[6:7], v[0:1], v[150:151] op_sel_hi:[1,0,1]
	v_mov_b32_e32 v0, v43
	v_pk_fma_f32 v[86:87], v[4:5], v[0:1], v[152:153] op_sel_hi:[1,0,1]
	v_pk_fma_f32 v[44:45], v[6:7], v[0:1], v[154:155] op_sel_hi:[1,0,1]
	v_mov_b32_e32 v0, v47
	v_pk_fma_f32 v[84:85], v[4:5], v[0:1], v[156:157] op_sel_hi:[1,0,1]
	v_pk_fma_f32 v[48:49], v[6:7], v[0:1], v[158:159] op_sel_hi:[1,0,1]
	v_mov_b32_e32 v0, v51
	v_pk_fma_f32 v[82:83], v[4:5], v[0:1], v[160:161] op_sel_hi:[1,0,1]
	v_pk_fma_f32 v[52:53], v[6:7], v[0:1], v[162:163] op_sel_hi:[1,0,1]
	v_mov_b32_e32 v0, v55
	v_pk_fma_f32 v[58:59], v[4:5], v[0:1], v[164:165] op_sel_hi:[1,0,1]
	v_pk_fma_f32 v[56:57], v[6:7], v[0:1], v[166:167] op_sel_hi:[1,0,1]
	v_mov_b32_e32 v0, v115
	v_pk_fma_f32 v[62:63], v[4:5], v[0:1], v[168:169] op_sel_hi:[1,0,1]
	v_pk_fma_f32 v[60:61], v[6:7], v[0:1], v[170:171] op_sel_hi:[1,0,1]
	v_mov_b32_e32 v0, v81
	v_pk_fma_f32 v[104:105], v[4:5], v[2:3], v[66:67] op_sel_hi:[1,0,1]
	v_pk_fma_f32 v[66:67], v[4:5], v[0:1], v[64:65] op_sel_hi:[1,0,1]
	v_pk_fma_f32 v[64:65], v[6:7], v[0:1], v[68:69] op_sel_hi:[1,0,1]
	v_mov_b32_e32 v0, v119
	v_pk_fma_f32 v[70:71], v[4:5], v[0:1], v[172:173] op_sel_hi:[1,0,1]
	v_pk_fma_f32 v[68:69], v[6:7], v[0:1], v[174:175] op_sel_hi:[1,0,1]
	v_mov_b32_e32 v0, v123
	v_pk_fma_f32 v[80:81], v[4:5], v[0:1], v[176:177] op_sel_hi:[1,0,1]
	v_pk_fma_f32 v[78:79], v[6:7], v[0:1], v[178:179] op_sel_hi:[1,0,1]
	v_lshl_add_u64 v[106:107], v[76:77], 0, s[68:69]
	v_add_co_u32_e32 v212, vcc, 0x30000, v106
	s_nop 1
	v_addc_co_u32_e32 v213, vcc, 0, v107, vcc
	global_load_dwordx4 v[180:183], v[212:213], off
	v_add_co_u32_e32 v212, vcc, 0x36000, v106
	s_nop 1
	v_addc_co_u32_e32 v213, vcc, 0, v107, vcc
	global_load_dwordx4 v[184:187], v[212:213], off
	v_add_co_u32_e32 v212, vcc, 0x3c000, v106
	s_nop 1
	v_addc_co_u32_e32 v213, vcc, 0, v107, vcc
	global_load_dwordx4 v[188:191], v[212:213], off
	v_add_co_u32_e32 v212, vcc, 0x42000, v106
	s_nop 1
	v_addc_co_u32_e32 v213, vcc, 0, v107, vcc
	global_load_dwordx4 v[192:195], v[212:213], off
	v_add_co_u32_e32 v212, vcc, 0x48000, v106
	s_nop 1
	v_addc_co_u32_e32 v213, vcc, 0, v107, vcc
	global_load_dwordx4 v[196:199], v[212:213], off
	v_add_co_u32_e32 v212, vcc, 0x4e000, v106
	s_nop 1
	v_addc_co_u32_e32 v213, vcc, 0, v107, vcc
	global_load_dwordx4 v[200:203], v[212:213], off
	v_add_co_u32_e32 v212, vcc, 0x54000, v106
	s_nop 1
	v_addc_co_u32_e32 v213, vcc, 0, v107, vcc
	global_load_dwordx4 v[204:207], v[212:213], off
	v_add_co_u32_e32 v212, vcc, 0x5a000, v106
	s_nop 1
	v_addc_co_u32_e32 v213, vcc, 0, v107, vcc
	global_load_dwordx4 v[208:211], v[212:213], off
	ds_read_b128 v[4:7], v72
	ds_read_b128 v[0:3], v72 offset:16
	s_mov_b32 s24, 0xc000
	s_add_u32 s68, s68, 0x30000
	s_addc_u32 s69, s69, 0
	s_cmp_eq_u32 s68, 0xc0000
	s_waitcnt vmcnt(8) lgkmcnt(1)
	v_mov_b64_e32 v[112:113], v[216:217]
	v_mov_b64_e32 v[114:115], v[218:219]
	v_pk_fma_f32 v[108:109], v[114:115], v[4:5], v[8:9] op_sel_hi:[1,0,1]
	ds_read_b128 v[8:11], v72 offset:2048
	v_pk_fma_f32 v[104:105], v[112:113], v[4:5], v[104:105] op_sel_hi:[1,0,1]
	s_waitcnt lgkmcnt(0)
	v_pk_fma_f32 v[116:117], v[114:115], v[8:9], v[12:13] op_sel_hi:[1,0,1]
	ds_read_b128 v[12:15], v72 offset:4096
	v_pk_fma_f32 v[102:103], v[112:113], v[8:9], v[102:103] op_sel_hi:[1,0,1]
	s_waitcnt lgkmcnt(0)
	v_pk_fma_f32 v[118:119], v[114:115], v[12:13], v[16:17] op_sel_hi:[1,0,1]
	ds_read_b128 v[16:19], v72 offset:6144
	v_pk_fma_f32 v[100:101], v[112:113], v[12:13], v[100:101] op_sel_hi:[1,0,1]
	s_waitcnt lgkmcnt(0)
	v_pk_fma_f32 v[120:121], v[114:115], v[16:17], v[20:21] op_sel_hi:[1,0,1]
	ds_read_b128 v[20:23], v72 offset:8192
	v_pk_fma_f32 v[98:99], v[112:113], v[16:17], v[98:99] op_sel_hi:[1,0,1]
	s_waitcnt lgkmcnt(0)
	v_pk_fma_f32 v[122:123], v[114:115], v[20:21], v[24:25] op_sel_hi:[1,0,1]
	ds_read_b128 v[24:27], v72 offset:10240
	v_pk_fma_f32 v[96:97], v[112:113], v[20:21], v[96:97] op_sel_hi:[1,0,1]
	s_waitcnt lgkmcnt(0)
	v_pk_fma_f32 v[124:125], v[114:115], v[24:25], v[28:29] op_sel_hi:[1,0,1]
	ds_read_b128 v[28:31], v72 offset:12288
	v_pk_fma_f32 v[94:95], v[112:113], v[24:25], v[94:95] op_sel_hi:[1,0,1]
	s_waitcnt lgkmcnt(0)
	v_pk_fma_f32 v[126:127], v[114:115], v[28:29], v[32:33] op_sel_hi:[1,0,1]
	ds_read_b128 v[32:35], v72 offset:14336
	v_pk_fma_f32 v[92:93], v[112:113], v[28:29], v[92:93] op_sel_hi:[1,0,1]
	s_waitcnt lgkmcnt(0)
	v_pk_fma_f32 v[128:129], v[114:115], v[32:33], v[36:37] op_sel_hi:[1,0,1]
	ds_read_b128 v[36:39], v72 offset:16384
	v_pk_fma_f32 v[90:91], v[112:113], v[32:33], v[90:91] op_sel_hi:[1,0,1]
	s_waitcnt lgkmcnt(0)
	v_pk_fma_f32 v[130:131], v[114:115], v[36:37], v[40:41] op_sel_hi:[1,0,1]
	ds_read_b128 v[40:43], v72 offset:18432
	v_pk_fma_f32 v[88:89], v[112:113], v[36:37], v[88:89] op_sel_hi:[1,0,1]
	s_waitcnt lgkmcnt(0)
	v_pk_fma_f32 v[132:133], v[114:115], v[40:41], v[44:45] op_sel_hi:[1,0,1]
	ds_read_b128 v[44:47], v72 offset:20480
	v_pk_fma_f32 v[86:87], v[112:113], v[40:41], v[86:87] op_sel_hi:[1,0,1]
	s_waitcnt lgkmcnt(0)
	v_pk_fma_f32 v[134:135], v[114:115], v[44:45], v[48:49] op_sel_hi:[1,0,1]
	ds_read_b128 v[48:51], v72 offset:22528
	v_pk_fma_f32 v[84:85], v[112:113], v[44:45], v[84:85] op_sel_hi:[1,0,1]
	s_waitcnt lgkmcnt(0)
	v_pk_fma_f32 v[136:137], v[114:115], v[48:49], v[52:53] op_sel_hi:[1,0,1]
	ds_read_b128 v[52:55], v72 offset:24576
	v_pk_fma_f32 v[82:83], v[112:113], v[48:49], v[82:83] op_sel_hi:[1,0,1]
	s_waitcnt lgkmcnt(0)
	v_pk_fma_f32 v[146:147], v[112:113], v[52:53], v[58:59] op_sel_hi:[1,0,1]
	v_pk_fma_f32 v[148:149], v[114:115], v[52:53], v[56:57] op_sel_hi:[1,0,1]
	ds_read_b128 v[56:59], v72 offset:26624
	s_waitcnt lgkmcnt(0)
	v_pk_fma_f32 v[150:151], v[112:113], v[56:57], v[62:63] op_sel_hi:[1,0,1]
	v_pk_fma_f32 v[152:153], v[114:115], v[56:57], v[60:61] op_sel_hi:[1,0,1]
	ds_read_b128 v[60:63], v72 offset:28672
	s_waitcnt lgkmcnt(0)
	v_pk_fma_f32 v[154:155], v[112:113], v[60:61], v[66:67] op_sel_hi:[1,0,1]
	v_pk_fma_f32 v[156:157], v[114:115], v[60:61], v[64:65] op_sel_hi:[1,0,1]
	ds_read_b128 v[64:67], v72 offset:30720
	s_waitcnt lgkmcnt(0)
	v_pk_fma_f32 v[158:159], v[112:113], v[64:65], v[70:71] op_sel_hi:[1,0,1]
	v_pk_fma_f32 v[160:161], v[114:115], v[64:65], v[68:69] op_sel_hi:[1,0,1]
	ds_read_b128 v[68:71], v72 offset:32768
	s_waitcnt lgkmcnt(0)
	v_pk_fma_f32 v[114:115], v[114:115], v[68:69], v[78:79] op_sel_hi:[1,0,1]
	v_add_co_u32_e32 v78, vcc, s75, v106
	v_pk_fma_f32 v[112:113], v[112:113], v[68:69], v[80:81] op_sel_hi:[1,0,1]
	s_nop 0
	v_addc_co_u32_e32 v79, vcc, 0, v107, vcc
	s_waitcnt vmcnt(8)
	v_mov_b64_e32 v[78:79], v[220:221]
	v_mov_b64_e32 v[80:81], v[222:223]
	v_pk_fma_f32 v[104:105], v[78:79], v[4:5], v[104:105] op_sel:[0,1,0]
	v_pk_fma_f32 v[4:5], v[80:81], v[4:5], v[108:109] op_sel:[0,1,0]
	v_pk_fma_f32 v[102:103], v[78:79], v[8:9], v[102:103] op_sel:[0,1,0]
	v_pk_fma_f32 v[8:9], v[80:81], v[8:9], v[116:117] op_sel:[0,1,0]
	v_pk_fma_f32 v[100:101], v[78:79], v[12:13], v[100:101] op_sel:[0,1,0]
	v_pk_fma_f32 v[12:13], v[80:81], v[12:13], v[118:119] op_sel:[0,1,0]
	v_pk_fma_f32 v[98:99], v[78:79], v[16:17], v[98:99] op_sel:[0,1,0]
	v_pk_fma_f32 v[16:17], v[80:81], v[16:17], v[120:121] op_sel:[0,1,0]
	v_pk_fma_f32 v[96:97], v[78:79], v[20:21], v[96:97] op_sel:[0,1,0]
	v_pk_fma_f32 v[94:95], v[78:79], v[24:25], v[94:95] op_sel:[0,1,0]
	v_pk_fma_f32 v[92:93], v[78:79], v[28:29], v[92:93] op_sel:[0,1,0]
	v_pk_fma_f32 v[90:91], v[78:79], v[32:33], v[90:91] op_sel:[0,1,0]
	v_pk_fma_f32 v[88:89], v[78:79], v[36:37], v[88:89] op_sel:[0,1,0]
	v_pk_fma_f32 v[86:87], v[78:79], v[40:41], v[86:87] op_sel:[0,1,0]
	v_pk_fma_f32 v[84:85], v[78:79], v[44:45], v[84:85] op_sel:[0,1,0]
	v_pk_fma_f32 v[82:83], v[78:79], v[48:49], v[82:83] op_sel:[0,1,0]
	v_pk_fma_f32 v[108:109], v[78:79], v[52:53], v[146:147] op_sel:[0,1,0]
	v_pk_fma_f32 v[116:117], v[78:79], v[56:57], v[150:151] op_sel:[0,1,0]
	v_pk_fma_f32 v[118:119], v[78:79], v[60:61], v[154:155] op_sel:[0,1,0]
	v_pk_fma_f32 v[120:121], v[78:79], v[64:65], v[158:159] op_sel:[0,1,0]
	v_pk_fma_f32 v[112:113], v[78:79], v[68:69], v[112:113] op_sel:[0,1,0]
	v_add_co_u32_e32 v78, vcc, s24, v106
	v_pk_fma_f32 v[20:21], v[80:81], v[20:21], v[122:123] op_sel:[0,1,0]
	s_nop 0
	v_addc_co_u32_e32 v79, vcc, 0, v107, vcc
	v_pk_fma_f32 v[24:25], v[80:81], v[24:25], v[124:125] op_sel:[0,1,0]
	v_pk_fma_f32 v[28:29], v[80:81], v[28:29], v[126:127] op_sel:[0,1,0]
	v_pk_fma_f32 v[32:33], v[80:81], v[32:33], v[128:129] op_sel:[0,1,0]
	v_pk_fma_f32 v[36:37], v[80:81], v[36:37], v[130:131] op_sel:[0,1,0]
	v_pk_fma_f32 v[40:41], v[80:81], v[40:41], v[132:133] op_sel:[0,1,0]
	v_pk_fma_f32 v[44:45], v[80:81], v[44:45], v[134:135] op_sel:[0,1,0]
	v_pk_fma_f32 v[48:49], v[80:81], v[48:49], v[136:137] op_sel:[0,1,0]
	v_pk_fma_f32 v[52:53], v[80:81], v[52:53], v[148:149] op_sel:[0,1,0]
	v_pk_fma_f32 v[56:57], v[80:81], v[56:57], v[152:153] op_sel:[0,1,0]
	v_pk_fma_f32 v[60:61], v[80:81], v[60:61], v[156:157] op_sel:[0,1,0]
	v_pk_fma_f32 v[64:65], v[80:81], v[64:65], v[160:161] op_sel:[0,1,0]
	v_pk_fma_f32 v[68:69], v[80:81], v[68:69], v[114:115] op_sel:[0,1,0]
	s_mov_b32 s24, 0x12000
	s_waitcnt vmcnt(8)
	v_mov_b64_e32 v[78:79], v[224:225]
	v_mov_b64_e32 v[80:81], v[226:227]
	v_pk_fma_f32 v[122:123], v[80:81], v[14:15], v[12:13] op_sel_hi:[1,0,1]
	v_add_co_u32_e32 v12, vcc, s24, v106
	v_pk_fma_f32 v[156:157], v[78:79], v[70:71], v[112:113] op_sel_hi:[1,0,1]
	s_nop 0
	v_addc_co_u32_e32 v13, vcc, 0, v107, vcc
	v_pk_fma_f32 v[104:105], v[78:79], v[6:7], v[104:105] op_sel_hi:[1,0,1]
	v_pk_fma_f32 v[4:5], v[80:81], v[6:7], v[4:5] op_sel_hi:[1,0,1]
	v_mov_b32_e32 v6, v7
	v_pk_fma_f32 v[102:103], v[78:79], v[10:11], v[102:103] op_sel_hi:[1,0,1]
	v_pk_fma_f32 v[8:9], v[80:81], v[10:11], v[8:9] op_sel_hi:[1,0,1]
	v_pk_fma_f32 v[100:101], v[78:79], v[14:15], v[100:101] op_sel_hi:[1,0,1]
	v_pk_fma_f32 v[150:151], v[78:79], v[54:55], v[108:109] op_sel_hi:[1,0,1]
	v_pk_fma_f32 v[98:99], v[78:79], v[18:19], v[98:99] op_sel_hi:[1,0,1]
	v_pk_fma_f32 v[124:125], v[80:81], v[18:19], v[16:17] op_sel_hi:[1,0,1]
	v_pk_fma_f32 v[96:97], v[78:79], v[22:23], v[96:97] op_sel_hi:[1,0,1]
	v_pk_fma_f32 v[126:127], v[80:81], v[22:23], v[20:21] op_sel_hi:[1,0,1]
	v_pk_fma_f32 v[94:95], v[78:79], v[26:27], v[94:95] op_sel_hi:[1,0,1]
	v_pk_fma_f32 v[128:129], v[80:81], v[26:27], v[24:25] op_sel_hi:[1,0,1]
	v_pk_fma_f32 v[92:93], v[78:79], v[30:31], v[92:93] op_sel_hi:[1,0,1]
	v_pk_fma_f32 v[130:131], v[80:81], v[30:31], v[28:29] op_sel_hi:[1,0,1]
	v_pk_fma_f32 v[90:91], v[78:79], v[34:35], v[90:91] op_sel_hi:[1,0,1]
	v_pk_fma_f32 v[132:133], v[80:81], v[34:35], v[32:33] op_sel_hi:[1,0,1]
	v_pk_fma_f32 v[88:89], v[78:79], v[38:39], v[88:89] op_sel_hi:[1,0,1]
	v_pk_fma_f32 v[134:135], v[80:81], v[38:39], v[36:37] op_sel_hi:[1,0,1]
	v_pk_fma_f32 v[86:87], v[78:79], v[42:43], v[86:87] op_sel_hi:[1,0,1]
	v_pk_fma_f32 v[136:137], v[80:81], v[42:43], v[40:41] op_sel_hi:[1,0,1]
	v_pk_fma_f32 v[84:85], v[78:79], v[46:47], v[84:85] op_sel_hi:[1,0,1]
	v_pk_fma_f32 v[146:147], v[80:81], v[46:47], v[44:45] op_sel_hi:[1,0,1]
	v_pk_fma_f32 v[82:83], v[78:79], v[50:51], v[82:83] op_sel_hi:[1,0,1]
	v_pk_fma_f32 v[148:149], v[80:81], v[50:51], v[48:49] op_sel_hi:[1,0,1]
	v_pk_fma_f32 v[152:153], v[80:81], v[54:55], v[52:53] op_sel_hi:[1,0,1]
	v_pk_fma_f32 v[116:117], v[78:79], v[58:59], v[116:117] op_sel_hi:[1,0,1]
	v_pk_fma_f32 v[56:57], v[80:81], v[58:59], v[56:57] op_sel_hi:[1,0,1]
	v_pk_fma_f32 v[118:119], v[78:79], v[62:63], v[118:119] op_sel_hi:[1,0,1]
	v_pk_fma_f32 v[60:61], v[80:81], v[62:63], v[60:61] op_sel_hi:[1,0,1]
	v_pk_fma_f32 v[120:121], v[78:79], v[66:67], v[120:121] op_sel_hi:[1,0,1]
	v_pk_fma_f32 v[154:155], v[80:81], v[66:67], v[64:65] op_sel_hi:[1,0,1]
	v_pk_fma_f32 v[158:159], v[80:81], v[70:71], v[68:69] op_sel_hi:[1,0,1]
	s_mov_b32 s24, 0x18000
	s_waitcnt vmcnt(8)
	v_mov_b64_e32 v[112:113], v[228:229]
	v_mov_b64_e32 v[114:115], v[230:231]
	v_pk_fma_f32 v[162:163], v[114:115], v[6:7], v[4:5] op_sel_hi:[1,0,1]
	v_mov_b32_e32 v4, v11
	v_pk_fma_f32 v[12:13], v[112:113], v[4:5], v[102:103] op_sel_hi:[1,0,1]
	v_pk_fma_f32 v[108:109], v[114:115], v[4:5], v[8:9] op_sel_hi:[1,0,1]
	v_mov_b32_e32 v4, v15
	v_pk_fma_f32 v[160:161], v[112:113], v[6:7], v[104:105] op_sel_hi:[1,0,1]
	v_pk_fma_f32 v[16:17], v[112:113], v[4:5], v[100:101] op_sel_hi:[1,0,1]
	v_pk_fma_f32 v[104:105], v[114:115], v[4:5], v[122:123] op_sel_hi:[1,0,1]
	v_mov_b32_e32 v4, v19
	v_pk_fma_f32 v[20:21], v[112:113], v[4:5], v[98:99] op_sel_hi:[1,0,1]
	v_pk_fma_f32 v[102:103], v[114:115], v[4:5], v[124:125] op_sel_hi:[1,0,1]
	v_mov_b32_e32 v4, v23
	v_pk_fma_f32 v[24:25], v[112:113], v[4:5], v[96:97] op_sel_hi:[1,0,1]
	v_pk_fma_f32 v[100:101], v[114:115], v[4:5], v[126:127] op_sel_hi:[1,0,1]
	v_mov_b32_e32 v4, v27
	v_pk_fma_f32 v[28:29], v[112:113], v[4:5], v[94:95] op_sel_hi:[1,0,1]
	v_pk_fma_f32 v[98:99], v[114:115], v[4:5], v[128:129] op_sel_hi:[1,0,1]
	v_mov_b32_e32 v4, v31
	v_pk_fma_f32 v[32:33], v[112:113], v[4:5], v[92:93] op_sel_hi:[1,0,1]
	v_pk_fma_f32 v[96:97], v[114:115], v[4:5], v[130:131] op_sel_hi:[1,0,1]
	v_mov_b32_e32 v4, v35
	v_pk_fma_f32 v[36:37], v[112:113], v[4:5], v[90:91] op_sel_hi:[1,0,1]
	v_pk_fma_f32 v[94:95], v[114:115], v[4:5], v[132:133] op_sel_hi:[1,0,1]
	v_mov_b32_e32 v4, v39
	v_pk_fma_f32 v[40:41], v[112:113], v[4:5], v[88:89] op_sel_hi:[1,0,1]
	v_pk_fma_f32 v[92:93], v[114:115], v[4:5], v[134:135] op_sel_hi:[1,0,1]
	v_mov_b32_e32 v4, v43
	v_pk_fma_f32 v[44:45], v[112:113], v[4:5], v[86:87] op_sel_hi:[1,0,1]
	v_pk_fma_f32 v[90:91], v[114:115], v[4:5], v[136:137] op_sel_hi:[1,0,1]
	v_mov_b32_e32 v4, v47
	v_pk_fma_f32 v[48:49], v[112:113], v[4:5], v[84:85] op_sel_hi:[1,0,1]
	v_pk_fma_f32 v[88:89], v[114:115], v[4:5], v[146:147] op_sel_hi:[1,0,1]
	v_mov_b32_e32 v4, v51
	v_pk_fma_f32 v[52:53], v[112:113], v[4:5], v[82:83] op_sel_hi:[1,0,1]
	v_pk_fma_f32 v[86:87], v[114:115], v[4:5], v[148:149] op_sel_hi:[1,0,1]
	v_mov_b32_e32 v4, v55
	v_pk_fma_f32 v[82:83], v[112:113], v[4:5], v[150:151] op_sel_hi:[1,0,1]
	v_pk_fma_f32 v[84:85], v[114:115], v[4:5], v[152:153] op_sel_hi:[1,0,1]
	v_mov_b32_e32 v4, v59
	v_pk_fma_f32 v[78:79], v[112:113], v[4:5], v[116:117] op_sel_hi:[1,0,1]
	v_pk_fma_f32 v[80:81], v[114:115], v[4:5], v[56:57] op_sel_hi:[1,0,1]
	v_mov_b32_e32 v4, v63
	v_pk_fma_f32 v[64:65], v[112:113], v[4:5], v[118:119] op_sel_hi:[1,0,1]
	v_pk_fma_f32 v[68:69], v[114:115], v[4:5], v[60:61] op_sel_hi:[1,0,1]
	v_mov_b32_e32 v4, v67
	v_pk_fma_f32 v[60:61], v[112:113], v[4:5], v[120:121] op_sel_hi:[1,0,1]
	v_pk_fma_f32 v[62:63], v[114:115], v[4:5], v[154:155] op_sel_hi:[1,0,1]
	v_mov_b32_e32 v4, v71
	v_pk_fma_f32 v[56:57], v[112:113], v[4:5], v[156:157] op_sel_hi:[1,0,1]
	v_pk_fma_f32 v[58:59], v[114:115], v[4:5], v[158:159] op_sel_hi:[1,0,1]
	v_add_co_u32_e32 v4, vcc, s24, v106
	ds_read_b128 v[8:11], v72 offset:2064
	ds_read_b128 v[120:123], v72 offset:32784
	v_addc_co_u32_e32 v5, vcc, 0, v107, vcc
	ds_read_b128 v[112:115], v72 offset:26640
	ds_read_b128 v[116:119], v72 offset:30736
	s_mov_b32 s24, 0x1e000
	s_waitcnt vmcnt(8) lgkmcnt(3)
	v_mov_b64_e32 v[4:5], v[232:233]
	v_mov_b64_e32 v[6:7], v[234:235]
	v_pk_fma_f32 v[124:125], v[4:5], v[8:9], v[12:13] op_sel_hi:[1,0,1]
	ds_read_b128 v[12:15], v72 offset:4112
	s_waitcnt lgkmcnt(2)
	v_pk_fma_f32 v[154:155], v[4:5], v[112:113], v[78:79] op_sel_hi:[1,0,1]
	v_pk_fma_f32 v[156:157], v[6:7], v[112:113], v[80:81] op_sel_hi:[1,0,1]
	ds_read_b128 v[78:81], v72 offset:28688
	v_pk_fma_f32 v[66:67], v[4:5], v[0:1], v[160:161] op_sel_hi:[1,0,1]
	s_waitcnt lgkmcnt(1)
	v_pk_fma_f32 v[126:127], v[4:5], v[12:13], v[16:17] op_sel_hi:[1,0,1]
	ds_read_b128 v[16:19], v72 offset:6160
	v_pk_fma_f32 v[60:61], v[4:5], v[116:117], v[60:61] op_sel_hi:[1,0,1]
	s_waitcnt lgkmcnt(1)
	v_pk_fma_f32 v[64:65], v[4:5], v[78:79], v[64:65] op_sel_hi:[1,0,1]
	v_pk_fma_f32 v[56:57], v[4:5], v[120:121], v[56:57] op_sel_hi:[1,0,1]
	v_pk_fma_f32 v[70:71], v[6:7], v[0:1], v[162:163] op_sel_hi:[1,0,1]
	s_waitcnt lgkmcnt(0)
	v_pk_fma_f32 v[128:129], v[4:5], v[16:17], v[20:21] op_sel_hi:[1,0,1]
	ds_read_b128 v[20:23], v72 offset:8208
	v_pk_fma_f32 v[108:109], v[6:7], v[8:9], v[108:109] op_sel_hi:[1,0,1]
	v_pk_fma_f32 v[104:105], v[6:7], v[12:13], v[104:105] op_sel_hi:[1,0,1]
	v_pk_fma_f32 v[102:103], v[6:7], v[16:17], v[102:103] op_sel_hi:[1,0,1]
	v_pk_fma_f32 v[68:69], v[6:7], v[78:79], v[68:69] op_sel_hi:[1,0,1]
	s_waitcnt lgkmcnt(0)
	v_pk_fma_f32 v[130:131], v[4:5], v[20:21], v[24:25] op_sel_hi:[1,0,1]
	ds_read_b128 v[24:27], v72 offset:10256
	v_pk_fma_f32 v[100:101], v[6:7], v[20:21], v[100:101] op_sel_hi:[1,0,1]
	v_pk_fma_f32 v[62:63], v[6:7], v[116:117], v[62:63] op_sel_hi:[1,0,1]
	v_pk_fma_f32 v[58:59], v[6:7], v[120:121], v[58:59] op_sel_hi:[1,0,1]
	s_waitcnt lgkmcnt(0)
	v_pk_fma_f32 v[132:133], v[4:5], v[24:25], v[28:29] op_sel_hi:[1,0,1]
	ds_read_b128 v[28:31], v72 offset:12304
	v_pk_fma_f32 v[98:99], v[6:7], v[24:25], v[98:99] op_sel_hi:[1,0,1]
	s_waitcnt lgkmcnt(0)
	v_pk_fma_f32 v[134:135], v[4:5], v[28:29], v[32:33] op_sel_hi:[1,0,1]
	ds_read_b128 v[32:35], v72 offset:14352
	v_pk_fma_f32 v[96:97], v[6:7], v[28:29], v[96:97] op_sel_hi:[1,0,1]
	s_waitcnt lgkmcnt(0)
	v_pk_fma_f32 v[136:137], v[4:5], v[32:33], v[36:37] op_sel_hi:[1,0,1]
	ds_read_b128 v[36:39], v72 offset:16400
	v_pk_fma_f32 v[94:95], v[6:7], v[32:33], v[94:95] op_sel_hi:[1,0,1]
	s_waitcnt lgkmcnt(0)
	v_pk_fma_f32 v[146:147], v[4:5], v[36:37], v[40:41] op_sel_hi:[1,0,1]
	ds_read_b128 v[40:43], v72 offset:18448
	v_pk_fma_f32 v[92:93], v[6:7], v[36:37], v[92:93] op_sel_hi:[1,0,1]
	s_waitcnt lgkmcnt(0)
	v_pk_fma_f32 v[148:149], v[4:5], v[40:41], v[44:45] op_sel_hi:[1,0,1]
	ds_read_b128 v[44:47], v72 offset:20496
	v_pk_fma_f32 v[90:91], v[6:7], v[40:41], v[90:91] op_sel_hi:[1,0,1]
	s_waitcnt lgkmcnt(0)
	v_pk_fma_f32 v[150:151], v[4:5], v[44:45], v[48:49] op_sel_hi:[1,0,1]
	ds_read_b128 v[48:51], v72 offset:22544
	v_pk_fma_f32 v[88:89], v[6:7], v[44:45], v[88:89] op_sel_hi:[1,0,1]
	s_waitcnt lgkmcnt(0)
	v_pk_fma_f32 v[152:153], v[4:5], v[48:49], v[52:53] op_sel_hi:[1,0,1]
	ds_read_b128 v[52:55], v72 offset:24592
	v_pk_fma_f32 v[86:87], v[6:7], v[48:49], v[86:87] op_sel_hi:[1,0,1]
	v_add_u32_e32 v72, 32, v72
	s_waitcnt lgkmcnt(0)
	v_pk_fma_f32 v[82:83], v[4:5], v[52:53], v[82:83] op_sel_hi:[1,0,1]
	v_add_co_u32_e32 v4, vcc, s24, v106
	v_pk_fma_f32 v[84:85], v[6:7], v[52:53], v[84:85] op_sel_hi:[1,0,1]
	s_nop 0
	v_addc_co_u32_e32 v5, vcc, 0, v107, vcc
	s_mov_b32 s24, 0x24000
	s_waitcnt vmcnt(8)
	v_mov_b64_e32 v[4:5], v[236:237]
	v_mov_b64_e32 v[6:7], v[238:239]
	v_pk_fma_f32 v[66:67], v[4:5], v[0:1], v[66:67] op_sel:[0,1,0]
	v_pk_fma_f32 v[0:1], v[6:7], v[0:1], v[70:71] op_sel:[0,1,0]
	v_pk_fma_f32 v[70:71], v[4:5], v[8:9], v[124:125] op_sel:[0,1,0]
	v_pk_fma_f32 v[8:9], v[6:7], v[8:9], v[108:109] op_sel:[0,1,0]
	v_pk_fma_f32 v[108:109], v[4:5], v[12:13], v[126:127] op_sel:[0,1,0]
	v_pk_fma_f32 v[12:13], v[6:7], v[12:13], v[104:105] op_sel:[0,1,0]
	v_pk_fma_f32 v[104:105], v[4:5], v[16:17], v[128:129] op_sel:[0,1,0]
	v_pk_fma_f32 v[16:17], v[6:7], v[16:17], v[102:103] op_sel:[0,1,0]
	v_pk_fma_f32 v[102:103], v[4:5], v[20:21], v[130:131] op_sel:[0,1,0]
	v_pk_fma_f32 v[20:21], v[6:7], v[20:21], v[100:101] op_sel:[0,1,0]
	v_pk_fma_f32 v[100:101], v[4:5], v[24:25], v[132:133] op_sel:[0,1,0]
	v_pk_fma_f32 v[24:25], v[6:7], v[24:25], v[98:99] op_sel:[0,1,0]
	v_pk_fma_f32 v[98:99], v[4:5], v[28:29], v[134:135] op_sel:[0,1,0]
	v_pk_fma_f32 v[28:29], v[6:7], v[28:29], v[96:97] op_sel:[0,1,0]
	v_pk_fma_f32 v[96:97], v[4:5], v[32:33], v[136:137] op_sel:[0,1,0]
	v_pk_fma_f32 v[32:33], v[6:7], v[32:33], v[94:95] op_sel:[0,1,0]
	v_pk_fma_f32 v[94:95], v[4:5], v[36:37], v[146:147] op_sel:[0,1,0]
	v_pk_fma_f32 v[36:37], v[6:7], v[36:37], v[92:93] op_sel:[0,1,0]
	v_pk_fma_f32 v[92:93], v[4:5], v[40:41], v[148:149] op_sel:[0,1,0]
	v_pk_fma_f32 v[40:41], v[6:7], v[40:41], v[90:91] op_sel:[0,1,0]
	v_pk_fma_f32 v[90:91], v[4:5], v[44:45], v[150:151] op_sel:[0,1,0]
	v_pk_fma_f32 v[44:45], v[6:7], v[44:45], v[88:89] op_sel:[0,1,0]
	v_pk_fma_f32 v[88:89], v[4:5], v[48:49], v[152:153] op_sel:[0,1,0]
	v_pk_fma_f32 v[82:83], v[4:5], v[52:53], v[82:83] op_sel:[0,1,0]
	v_pk_fma_f32 v[52:53], v[6:7], v[52:53], v[84:85] op_sel:[0,1,0]
	v_pk_fma_f32 v[84:85], v[4:5], v[112:113], v[154:155] op_sel:[0,1,0]
	v_pk_fma_f32 v[64:65], v[4:5], v[78:79], v[64:65] op_sel:[0,1,0]
	v_pk_fma_f32 v[60:61], v[4:5], v[116:117], v[60:61] op_sel:[0,1,0]
	v_pk_fma_f32 v[56:57], v[4:5], v[120:121], v[56:57] op_sel:[0,1,0]
	v_add_co_u32_e32 v4, vcc, s24, v106
	v_pk_fma_f32 v[48:49], v[6:7], v[48:49], v[86:87] op_sel:[0,1,0]
	s_nop 0
	v_addc_co_u32_e32 v5, vcc, 0, v107, vcc
	v_pk_fma_f32 v[86:87], v[6:7], v[112:113], v[156:157] op_sel:[0,1,0]
	v_pk_fma_f32 v[68:69], v[6:7], v[78:79], v[68:69] op_sel:[0,1,0]
	v_pk_fma_f32 v[62:63], v[6:7], v[116:117], v[62:63] op_sel:[0,1,0]
	v_pk_fma_f32 v[58:59], v[6:7], v[120:121], v[58:59] op_sel:[0,1,0]
	s_mov_b32 s24, 0x2a000
	s_waitcnt vmcnt(8)
	v_mov_b64_e32 v[4:5], v[240:241]
	v_mov_b64_e32 v[6:7], v[242:243]
	v_pk_fma_f32 v[66:67], v[4:5], v[2:3], v[66:67] op_sel_hi:[1,0,1]
	v_pk_fma_f32 v[70:71], v[4:5], v[10:11], v[70:71] op_sel_hi:[1,0,1]
	v_pk_fma_f32 v[108:109], v[4:5], v[14:15], v[108:109] op_sel_hi:[1,0,1]
	v_pk_fma_f32 v[116:117], v[4:5], v[18:19], v[104:105] op_sel_hi:[1,0,1]
	v_pk_fma_f32 v[124:125], v[4:5], v[22:23], v[102:103] op_sel_hi:[1,0,1]
	v_pk_fma_f32 v[128:129], v[4:5], v[26:27], v[100:101] op_sel_hi:[1,0,1]
	v_pk_fma_f32 v[132:133], v[4:5], v[30:31], v[98:99] op_sel_hi:[1,0,1]
	v_pk_fma_f32 v[136:137], v[4:5], v[34:35], v[96:97] op_sel_hi:[1,0,1]
	v_pk_fma_f32 v[148:149], v[4:5], v[38:39], v[94:95] op_sel_hi:[1,0,1]
	v_pk_fma_f32 v[152:153], v[4:5], v[42:43], v[92:93] op_sel_hi:[1,0,1]
	v_pk_fma_f32 v[156:157], v[4:5], v[46:47], v[90:91] op_sel_hi:[1,0,1]
	v_pk_fma_f32 v[160:161], v[4:5], v[50:51], v[88:89] op_sel_hi:[1,0,1]
	v_pk_fma_f32 v[164:165], v[4:5], v[54:55], v[82:83] op_sel_hi:[1,0,1]
	v_pk_fma_f32 v[168:169], v[4:5], v[114:115], v[84:85] op_sel_hi:[1,0,1]
	v_pk_fma_f32 v[64:65], v[4:5], v[80:81], v[64:65] op_sel_hi:[1,0,1]
	v_pk_fma_f32 v[172:173], v[4:5], v[118:119], v[60:61] op_sel_hi:[1,0,1]
	v_pk_fma_f32 v[176:177], v[4:5], v[122:123], v[56:57] op_sel_hi:[1,0,1]
	v_add_co_u32_e32 v4, vcc, s24, v106
	v_pk_fma_f32 v[0:1], v[6:7], v[2:3], v[0:1] op_sel_hi:[1,0,1]
	s_nop 0
	v_addc_co_u32_e32 v5, vcc, 0, v107, vcc
	v_pk_fma_f32 v[78:79], v[6:7], v[10:11], v[8:9] op_sel_hi:[1,0,1]
	v_pk_fma_f32 v[112:113], v[6:7], v[14:15], v[12:13] op_sel_hi:[1,0,1]
	v_pk_fma_f32 v[120:121], v[6:7], v[18:19], v[16:17] op_sel_hi:[1,0,1]
	v_pk_fma_f32 v[126:127], v[6:7], v[22:23], v[20:21] op_sel_hi:[1,0,1]
	v_pk_fma_f32 v[130:131], v[6:7], v[26:27], v[24:25] op_sel_hi:[1,0,1]
	v_pk_fma_f32 v[134:135], v[6:7], v[30:31], v[28:29] op_sel_hi:[1,0,1]
	v_pk_fma_f32 v[146:147], v[6:7], v[34:35], v[32:33] op_sel_hi:[1,0,1]
	v_pk_fma_f32 v[150:151], v[6:7], v[38:39], v[36:37] op_sel_hi:[1,0,1]
	v_pk_fma_f32 v[154:155], v[6:7], v[42:43], v[40:41] op_sel_hi:[1,0,1]
	v_pk_fma_f32 v[158:159], v[6:7], v[46:47], v[44:45] op_sel_hi:[1,0,1]
	v_pk_fma_f32 v[162:163], v[6:7], v[50:51], v[48:49] op_sel_hi:[1,0,1]
	v_pk_fma_f32 v[166:167], v[6:7], v[54:55], v[52:53] op_sel_hi:[1,0,1]
	v_pk_fma_f32 v[170:171], v[6:7], v[114:115], v[86:87] op_sel_hi:[1,0,1]
	v_pk_fma_f32 v[68:69], v[6:7], v[80:81], v[68:69] op_sel_hi:[1,0,1]
	v_pk_fma_f32 v[174:175], v[6:7], v[118:119], v[62:63] op_sel_hi:[1,0,1]
	v_pk_fma_f32 v[178:179], v[6:7], v[122:123], v[58:59] op_sel_hi:[1,0,1]
	v_mov_b32_e32 v2, v3
	s_waitcnt vmcnt(8)
	v_mov_b64_e32 v[4:5], v[244:245]
	v_mov_b64_e32 v[6:7], v[246:247]
	v_pk_fma_f32 v[8:9], v[6:7], v[2:3], v[0:1] op_sel_hi:[1,0,1]
	v_mov_b32_e32 v0, v11
	v_pk_fma_f32 v[102:103], v[4:5], v[0:1], v[70:71] op_sel_hi:[1,0,1]
	v_pk_fma_f32 v[12:13], v[6:7], v[0:1], v[78:79] op_sel_hi:[1,0,1]
	v_mov_b32_e32 v0, v15
	v_pk_fma_f32 v[100:101], v[4:5], v[0:1], v[108:109] op_sel_hi:[1,0,1]
	v_pk_fma_f32 v[16:17], v[6:7], v[0:1], v[112:113] op_sel_hi:[1,0,1]
	v_mov_b32_e32 v0, v19
	v_pk_fma_f32 v[98:99], v[4:5], v[0:1], v[116:117] op_sel_hi:[1,0,1]
	v_pk_fma_f32 v[20:21], v[6:7], v[0:1], v[120:121] op_sel_hi:[1,0,1]
	v_mov_b32_e32 v0, v23
	v_pk_fma_f32 v[96:97], v[4:5], v[0:1], v[124:125] op_sel_hi:[1,0,1]
	v_pk_fma_f32 v[24:25], v[6:7], v[0:1], v[126:127] op_sel_hi:[1,0,1]
	v_mov_b32_e32 v0, v27
	v_pk_fma_f32 v[94:95], v[4:5], v[0:1], v[128:129] op_sel_hi:[1,0,1]
	v_pk_fma_f32 v[28:29], v[6:7], v[0:1], v[130:131] op_sel_hi:[1,0,1]
	v_mov_b32_e32 v0, v31
	v_pk_fma_f32 v[92:93], v[4:5], v[0:1], v[132:133] op_sel_hi:[1,0,1]
	v_pk_fma_f32 v[32:33], v[6:7], v[0:1], v[134:135] op_sel_hi:[1,0,1]
	v_mov_b32_e32 v0, v35
	v_pk_fma_f32 v[90:91], v[4:5], v[0:1], v[136:137] op_sel_hi:[1,0,1]
	v_pk_fma_f32 v[36:37], v[6:7], v[0:1], v[146:147] op_sel_hi:[1,0,1]
	v_mov_b32_e32 v0, v39
	v_pk_fma_f32 v[88:89], v[4:5], v[0:1], v[148:149] op_sel_hi:[1,0,1]
	v_pk_fma_f32 v[40:41], v[6:7], v[0:1], v[150:151] op_sel_hi:[1,0,1]
	v_mov_b32_e32 v0, v43
	v_pk_fma_f32 v[86:87], v[4:5], v[0:1], v[152:153] op_sel_hi:[1,0,1]
	v_pk_fma_f32 v[44:45], v[6:7], v[0:1], v[154:155] op_sel_hi:[1,0,1]
	v_mov_b32_e32 v0, v47
	v_pk_fma_f32 v[84:85], v[4:5], v[0:1], v[156:157] op_sel_hi:[1,0,1]
	v_pk_fma_f32 v[48:49], v[6:7], v[0:1], v[158:159] op_sel_hi:[1,0,1]
	v_mov_b32_e32 v0, v51
	v_pk_fma_f32 v[82:83], v[4:5], v[0:1], v[160:161] op_sel_hi:[1,0,1]
	v_pk_fma_f32 v[52:53], v[6:7], v[0:1], v[162:163] op_sel_hi:[1,0,1]
	v_mov_b32_e32 v0, v55
	v_pk_fma_f32 v[58:59], v[4:5], v[0:1], v[164:165] op_sel_hi:[1,0,1]
	v_pk_fma_f32 v[56:57], v[6:7], v[0:1], v[166:167] op_sel_hi:[1,0,1]
	v_mov_b32_e32 v0, v115
	v_pk_fma_f32 v[62:63], v[4:5], v[0:1], v[168:169] op_sel_hi:[1,0,1]
	v_pk_fma_f32 v[60:61], v[6:7], v[0:1], v[170:171] op_sel_hi:[1,0,1]
	v_mov_b32_e32 v0, v81
	v_pk_fma_f32 v[104:105], v[4:5], v[2:3], v[66:67] op_sel_hi:[1,0,1]
	v_pk_fma_f32 v[66:67], v[4:5], v[0:1], v[64:65] op_sel_hi:[1,0,1]
	v_pk_fma_f32 v[64:65], v[6:7], v[0:1], v[68:69] op_sel_hi:[1,0,1]
	v_mov_b32_e32 v0, v119
	v_pk_fma_f32 v[70:71], v[4:5], v[0:1], v[172:173] op_sel_hi:[1,0,1]
	v_pk_fma_f32 v[68:69], v[6:7], v[0:1], v[174:175] op_sel_hi:[1,0,1]
	v_mov_b32_e32 v0, v123
	v_pk_fma_f32 v[80:81], v[4:5], v[0:1], v[176:177] op_sel_hi:[1,0,1]
	v_pk_fma_f32 v[78:79], v[6:7], v[0:1], v[178:179] op_sel_hi:[1,0,1]
	v_lshl_add_u64 v[106:107], v[76:77], 0, s[68:69]
	ds_read_b128 v[4:7], v72
	ds_read_b128 v[0:3], v72 offset:16
	s_mov_b32 s24, 0xc000
	s_add_u32 s68, s68, 0x30000
	s_addc_u32 s69, s69, 0
	s_cmp_eq_u32 s68, 0xc0000
	s_waitcnt vmcnt(0) lgkmcnt(1)
	v_mov_b64_e32 v[112:113], v[180:181]
	v_mov_b64_e32 v[114:115], v[182:183]
	v_pk_fma_f32 v[108:109], v[114:115], v[4:5], v[8:9] op_sel_hi:[1,0,1]
	ds_read_b128 v[8:11], v72 offset:2048
	v_pk_fma_f32 v[104:105], v[112:113], v[4:5], v[104:105] op_sel_hi:[1,0,1]
	s_waitcnt lgkmcnt(0)
	v_pk_fma_f32 v[116:117], v[114:115], v[8:9], v[12:13] op_sel_hi:[1,0,1]
	ds_read_b128 v[12:15], v72 offset:4096
	v_pk_fma_f32 v[102:103], v[112:113], v[8:9], v[102:103] op_sel_hi:[1,0,1]
	s_waitcnt lgkmcnt(0)
	v_pk_fma_f32 v[118:119], v[114:115], v[12:13], v[16:17] op_sel_hi:[1,0,1]
	ds_read_b128 v[16:19], v72 offset:6144
	v_pk_fma_f32 v[100:101], v[112:113], v[12:13], v[100:101] op_sel_hi:[1,0,1]
	s_waitcnt lgkmcnt(0)
	v_pk_fma_f32 v[120:121], v[114:115], v[16:17], v[20:21] op_sel_hi:[1,0,1]
	ds_read_b128 v[20:23], v72 offset:8192
	v_pk_fma_f32 v[98:99], v[112:113], v[16:17], v[98:99] op_sel_hi:[1,0,1]
	s_waitcnt lgkmcnt(0)
	v_pk_fma_f32 v[122:123], v[114:115], v[20:21], v[24:25] op_sel_hi:[1,0,1]
	ds_read_b128 v[24:27], v72 offset:10240
	v_pk_fma_f32 v[96:97], v[112:113], v[20:21], v[96:97] op_sel_hi:[1,0,1]
	s_waitcnt lgkmcnt(0)
	v_pk_fma_f32 v[124:125], v[114:115], v[24:25], v[28:29] op_sel_hi:[1,0,1]
	ds_read_b128 v[28:31], v72 offset:12288
	v_pk_fma_f32 v[94:95], v[112:113], v[24:25], v[94:95] op_sel_hi:[1,0,1]
	s_waitcnt lgkmcnt(0)
	v_pk_fma_f32 v[126:127], v[114:115], v[28:29], v[32:33] op_sel_hi:[1,0,1]
	ds_read_b128 v[32:35], v72 offset:14336
	v_pk_fma_f32 v[92:93], v[112:113], v[28:29], v[92:93] op_sel_hi:[1,0,1]
	s_waitcnt lgkmcnt(0)
	v_pk_fma_f32 v[128:129], v[114:115], v[32:33], v[36:37] op_sel_hi:[1,0,1]
	ds_read_b128 v[36:39], v72 offset:16384
	v_pk_fma_f32 v[90:91], v[112:113], v[32:33], v[90:91] op_sel_hi:[1,0,1]
	s_waitcnt lgkmcnt(0)
	v_pk_fma_f32 v[130:131], v[114:115], v[36:37], v[40:41] op_sel_hi:[1,0,1]
	ds_read_b128 v[40:43], v72 offset:18432
	v_pk_fma_f32 v[88:89], v[112:113], v[36:37], v[88:89] op_sel_hi:[1,0,1]
	s_waitcnt lgkmcnt(0)
	v_pk_fma_f32 v[132:133], v[114:115], v[40:41], v[44:45] op_sel_hi:[1,0,1]
	ds_read_b128 v[44:47], v72 offset:20480
	v_pk_fma_f32 v[86:87], v[112:113], v[40:41], v[86:87] op_sel_hi:[1,0,1]
	s_waitcnt lgkmcnt(0)
	v_pk_fma_f32 v[134:135], v[114:115], v[44:45], v[48:49] op_sel_hi:[1,0,1]
	ds_read_b128 v[48:51], v72 offset:22528
	v_pk_fma_f32 v[84:85], v[112:113], v[44:45], v[84:85] op_sel_hi:[1,0,1]
	s_waitcnt lgkmcnt(0)
	v_pk_fma_f32 v[136:137], v[114:115], v[48:49], v[52:53] op_sel_hi:[1,0,1]
	ds_read_b128 v[52:55], v72 offset:24576
	v_pk_fma_f32 v[82:83], v[112:113], v[48:49], v[82:83] op_sel_hi:[1,0,1]
	s_waitcnt lgkmcnt(0)
	v_pk_fma_f32 v[146:147], v[112:113], v[52:53], v[58:59] op_sel_hi:[1,0,1]
	v_pk_fma_f32 v[148:149], v[114:115], v[52:53], v[56:57] op_sel_hi:[1,0,1]
	ds_read_b128 v[56:59], v72 offset:26624
	s_waitcnt lgkmcnt(0)
	v_pk_fma_f32 v[150:151], v[112:113], v[56:57], v[62:63] op_sel_hi:[1,0,1]
	v_pk_fma_f32 v[152:153], v[114:115], v[56:57], v[60:61] op_sel_hi:[1,0,1]
	ds_read_b128 v[60:63], v72 offset:28672
	s_waitcnt lgkmcnt(0)
	v_pk_fma_f32 v[154:155], v[112:113], v[60:61], v[66:67] op_sel_hi:[1,0,1]
	v_pk_fma_f32 v[156:157], v[114:115], v[60:61], v[64:65] op_sel_hi:[1,0,1]
	ds_read_b128 v[64:67], v72 offset:30720
	s_waitcnt lgkmcnt(0)
	v_pk_fma_f32 v[158:159], v[112:113], v[64:65], v[70:71] op_sel_hi:[1,0,1]
	v_pk_fma_f32 v[160:161], v[114:115], v[64:65], v[68:69] op_sel_hi:[1,0,1]
	ds_read_b128 v[68:71], v72 offset:32768
	s_waitcnt lgkmcnt(0)
	v_pk_fma_f32 v[114:115], v[114:115], v[68:69], v[78:79] op_sel_hi:[1,0,1]
	v_add_co_u32_e32 v78, vcc, s75, v106
	v_pk_fma_f32 v[112:113], v[112:113], v[68:69], v[80:81] op_sel_hi:[1,0,1]
	s_nop 0
	v_addc_co_u32_e32 v79, vcc, 0, v107, vcc
	s_waitcnt vmcnt(0)
	v_mov_b64_e32 v[78:79], v[184:185]
	v_mov_b64_e32 v[80:81], v[186:187]
	v_pk_fma_f32 v[104:105], v[78:79], v[4:5], v[104:105] op_sel:[0,1,0]
	v_pk_fma_f32 v[4:5], v[80:81], v[4:5], v[108:109] op_sel:[0,1,0]
	v_pk_fma_f32 v[102:103], v[78:79], v[8:9], v[102:103] op_sel:[0,1,0]
	v_pk_fma_f32 v[8:9], v[80:81], v[8:9], v[116:117] op_sel:[0,1,0]
	v_pk_fma_f32 v[100:101], v[78:79], v[12:13], v[100:101] op_sel:[0,1,0]
	v_pk_fma_f32 v[12:13], v[80:81], v[12:13], v[118:119] op_sel:[0,1,0]
	v_pk_fma_f32 v[98:99], v[78:79], v[16:17], v[98:99] op_sel:[0,1,0]
	v_pk_fma_f32 v[16:17], v[80:81], v[16:17], v[120:121] op_sel:[0,1,0]
	v_pk_fma_f32 v[96:97], v[78:79], v[20:21], v[96:97] op_sel:[0,1,0]
	v_pk_fma_f32 v[94:95], v[78:79], v[24:25], v[94:95] op_sel:[0,1,0]
	v_pk_fma_f32 v[92:93], v[78:79], v[28:29], v[92:93] op_sel:[0,1,0]
	v_pk_fma_f32 v[90:91], v[78:79], v[32:33], v[90:91] op_sel:[0,1,0]
	v_pk_fma_f32 v[88:89], v[78:79], v[36:37], v[88:89] op_sel:[0,1,0]
	v_pk_fma_f32 v[86:87], v[78:79], v[40:41], v[86:87] op_sel:[0,1,0]
	v_pk_fma_f32 v[84:85], v[78:79], v[44:45], v[84:85] op_sel:[0,1,0]
	v_pk_fma_f32 v[82:83], v[78:79], v[48:49], v[82:83] op_sel:[0,1,0]
	v_pk_fma_f32 v[108:109], v[78:79], v[52:53], v[146:147] op_sel:[0,1,0]
	v_pk_fma_f32 v[116:117], v[78:79], v[56:57], v[150:151] op_sel:[0,1,0]
	v_pk_fma_f32 v[118:119], v[78:79], v[60:61], v[154:155] op_sel:[0,1,0]
	v_pk_fma_f32 v[120:121], v[78:79], v[64:65], v[158:159] op_sel:[0,1,0]
	v_pk_fma_f32 v[112:113], v[78:79], v[68:69], v[112:113] op_sel:[0,1,0]
	v_add_co_u32_e32 v78, vcc, s24, v106
	v_pk_fma_f32 v[20:21], v[80:81], v[20:21], v[122:123] op_sel:[0,1,0]
	s_nop 0
	v_addc_co_u32_e32 v79, vcc, 0, v107, vcc
	v_pk_fma_f32 v[24:25], v[80:81], v[24:25], v[124:125] op_sel:[0,1,0]
	v_pk_fma_f32 v[28:29], v[80:81], v[28:29], v[126:127] op_sel:[0,1,0]
	v_pk_fma_f32 v[32:33], v[80:81], v[32:33], v[128:129] op_sel:[0,1,0]
	v_pk_fma_f32 v[36:37], v[80:81], v[36:37], v[130:131] op_sel:[0,1,0]
	v_pk_fma_f32 v[40:41], v[80:81], v[40:41], v[132:133] op_sel:[0,1,0]
	v_pk_fma_f32 v[44:45], v[80:81], v[44:45], v[134:135] op_sel:[0,1,0]
	v_pk_fma_f32 v[48:49], v[80:81], v[48:49], v[136:137] op_sel:[0,1,0]
	v_pk_fma_f32 v[52:53], v[80:81], v[52:53], v[148:149] op_sel:[0,1,0]
	v_pk_fma_f32 v[56:57], v[80:81], v[56:57], v[152:153] op_sel:[0,1,0]
	v_pk_fma_f32 v[60:61], v[80:81], v[60:61], v[156:157] op_sel:[0,1,0]
	v_pk_fma_f32 v[64:65], v[80:81], v[64:65], v[160:161] op_sel:[0,1,0]
	v_pk_fma_f32 v[68:69], v[80:81], v[68:69], v[114:115] op_sel:[0,1,0]
	s_mov_b32 s24, 0x12000
	s_waitcnt vmcnt(0)
	v_mov_b64_e32 v[78:79], v[188:189]
	v_mov_b64_e32 v[80:81], v[190:191]
	v_pk_fma_f32 v[122:123], v[80:81], v[14:15], v[12:13] op_sel_hi:[1,0,1]
	v_add_co_u32_e32 v12, vcc, s24, v106
	v_pk_fma_f32 v[156:157], v[78:79], v[70:71], v[112:113] op_sel_hi:[1,0,1]
	s_nop 0
	v_addc_co_u32_e32 v13, vcc, 0, v107, vcc
	v_pk_fma_f32 v[104:105], v[78:79], v[6:7], v[104:105] op_sel_hi:[1,0,1]
	v_pk_fma_f32 v[4:5], v[80:81], v[6:7], v[4:5] op_sel_hi:[1,0,1]
	v_mov_b32_e32 v6, v7
	v_pk_fma_f32 v[102:103], v[78:79], v[10:11], v[102:103] op_sel_hi:[1,0,1]
	v_pk_fma_f32 v[8:9], v[80:81], v[10:11], v[8:9] op_sel_hi:[1,0,1]
	v_pk_fma_f32 v[100:101], v[78:79], v[14:15], v[100:101] op_sel_hi:[1,0,1]
	v_pk_fma_f32 v[150:151], v[78:79], v[54:55], v[108:109] op_sel_hi:[1,0,1]
	v_pk_fma_f32 v[98:99], v[78:79], v[18:19], v[98:99] op_sel_hi:[1,0,1]
	v_pk_fma_f32 v[124:125], v[80:81], v[18:19], v[16:17] op_sel_hi:[1,0,1]
	v_pk_fma_f32 v[96:97], v[78:79], v[22:23], v[96:97] op_sel_hi:[1,0,1]
	v_pk_fma_f32 v[126:127], v[80:81], v[22:23], v[20:21] op_sel_hi:[1,0,1]
	v_pk_fma_f32 v[94:95], v[78:79], v[26:27], v[94:95] op_sel_hi:[1,0,1]
	v_pk_fma_f32 v[128:129], v[80:81], v[26:27], v[24:25] op_sel_hi:[1,0,1]
	v_pk_fma_f32 v[92:93], v[78:79], v[30:31], v[92:93] op_sel_hi:[1,0,1]
	v_pk_fma_f32 v[130:131], v[80:81], v[30:31], v[28:29] op_sel_hi:[1,0,1]
	v_pk_fma_f32 v[90:91], v[78:79], v[34:35], v[90:91] op_sel_hi:[1,0,1]
	v_pk_fma_f32 v[132:133], v[80:81], v[34:35], v[32:33] op_sel_hi:[1,0,1]
	v_pk_fma_f32 v[88:89], v[78:79], v[38:39], v[88:89] op_sel_hi:[1,0,1]
	v_pk_fma_f32 v[134:135], v[80:81], v[38:39], v[36:37] op_sel_hi:[1,0,1]
	v_pk_fma_f32 v[86:87], v[78:79], v[42:43], v[86:87] op_sel_hi:[1,0,1]
	v_pk_fma_f32 v[136:137], v[80:81], v[42:43], v[40:41] op_sel_hi:[1,0,1]
	v_pk_fma_f32 v[84:85], v[78:79], v[46:47], v[84:85] op_sel_hi:[1,0,1]
	v_pk_fma_f32 v[146:147], v[80:81], v[46:47], v[44:45] op_sel_hi:[1,0,1]
	v_pk_fma_f32 v[82:83], v[78:79], v[50:51], v[82:83] op_sel_hi:[1,0,1]
	v_pk_fma_f32 v[148:149], v[80:81], v[50:51], v[48:49] op_sel_hi:[1,0,1]
	v_pk_fma_f32 v[152:153], v[80:81], v[54:55], v[52:53] op_sel_hi:[1,0,1]
	v_pk_fma_f32 v[116:117], v[78:79], v[58:59], v[116:117] op_sel_hi:[1,0,1]
	v_pk_fma_f32 v[56:57], v[80:81], v[58:59], v[56:57] op_sel_hi:[1,0,1]
	v_pk_fma_f32 v[118:119], v[78:79], v[62:63], v[118:119] op_sel_hi:[1,0,1]
	v_pk_fma_f32 v[60:61], v[80:81], v[62:63], v[60:61] op_sel_hi:[1,0,1]
	v_pk_fma_f32 v[120:121], v[78:79], v[66:67], v[120:121] op_sel_hi:[1,0,1]
	v_pk_fma_f32 v[154:155], v[80:81], v[66:67], v[64:65] op_sel_hi:[1,0,1]
	v_pk_fma_f32 v[158:159], v[80:81], v[70:71], v[68:69] op_sel_hi:[1,0,1]
	s_mov_b32 s24, 0x18000
	s_waitcnt vmcnt(0)
	v_mov_b64_e32 v[112:113], v[192:193]
	v_mov_b64_e32 v[114:115], v[194:195]
	v_pk_fma_f32 v[162:163], v[114:115], v[6:7], v[4:5] op_sel_hi:[1,0,1]
	v_mov_b32_e32 v4, v11
	v_pk_fma_f32 v[12:13], v[112:113], v[4:5], v[102:103] op_sel_hi:[1,0,1]
	v_pk_fma_f32 v[108:109], v[114:115], v[4:5], v[8:9] op_sel_hi:[1,0,1]
	v_mov_b32_e32 v4, v15
	v_pk_fma_f32 v[160:161], v[112:113], v[6:7], v[104:105] op_sel_hi:[1,0,1]
	v_pk_fma_f32 v[16:17], v[112:113], v[4:5], v[100:101] op_sel_hi:[1,0,1]
	v_pk_fma_f32 v[104:105], v[114:115], v[4:5], v[122:123] op_sel_hi:[1,0,1]
	v_mov_b32_e32 v4, v19
	v_pk_fma_f32 v[20:21], v[112:113], v[4:5], v[98:99] op_sel_hi:[1,0,1]
	v_pk_fma_f32 v[102:103], v[114:115], v[4:5], v[124:125] op_sel_hi:[1,0,1]
	v_mov_b32_e32 v4, v23
	v_pk_fma_f32 v[24:25], v[112:113], v[4:5], v[96:97] op_sel_hi:[1,0,1]
	v_pk_fma_f32 v[100:101], v[114:115], v[4:5], v[126:127] op_sel_hi:[1,0,1]
	v_mov_b32_e32 v4, v27
	v_pk_fma_f32 v[28:29], v[112:113], v[4:5], v[94:95] op_sel_hi:[1,0,1]
	v_pk_fma_f32 v[98:99], v[114:115], v[4:5], v[128:129] op_sel_hi:[1,0,1]
	v_mov_b32_e32 v4, v31
	v_pk_fma_f32 v[32:33], v[112:113], v[4:5], v[92:93] op_sel_hi:[1,0,1]
	v_pk_fma_f32 v[96:97], v[114:115], v[4:5], v[130:131] op_sel_hi:[1,0,1]
	v_mov_b32_e32 v4, v35
	v_pk_fma_f32 v[36:37], v[112:113], v[4:5], v[90:91] op_sel_hi:[1,0,1]
	v_pk_fma_f32 v[94:95], v[114:115], v[4:5], v[132:133] op_sel_hi:[1,0,1]
	v_mov_b32_e32 v4, v39
	v_pk_fma_f32 v[40:41], v[112:113], v[4:5], v[88:89] op_sel_hi:[1,0,1]
	v_pk_fma_f32 v[92:93], v[114:115], v[4:5], v[134:135] op_sel_hi:[1,0,1]
	v_mov_b32_e32 v4, v43
	v_pk_fma_f32 v[44:45], v[112:113], v[4:5], v[86:87] op_sel_hi:[1,0,1]
	v_pk_fma_f32 v[90:91], v[114:115], v[4:5], v[136:137] op_sel_hi:[1,0,1]
	v_mov_b32_e32 v4, v47
	v_pk_fma_f32 v[48:49], v[112:113], v[4:5], v[84:85] op_sel_hi:[1,0,1]
	v_pk_fma_f32 v[88:89], v[114:115], v[4:5], v[146:147] op_sel_hi:[1,0,1]
	v_mov_b32_e32 v4, v51
	v_pk_fma_f32 v[52:53], v[112:113], v[4:5], v[82:83] op_sel_hi:[1,0,1]
	v_pk_fma_f32 v[86:87], v[114:115], v[4:5], v[148:149] op_sel_hi:[1,0,1]
	v_mov_b32_e32 v4, v55
	v_pk_fma_f32 v[82:83], v[112:113], v[4:5], v[150:151] op_sel_hi:[1,0,1]
	v_pk_fma_f32 v[84:85], v[114:115], v[4:5], v[152:153] op_sel_hi:[1,0,1]
	v_mov_b32_e32 v4, v59
	v_pk_fma_f32 v[78:79], v[112:113], v[4:5], v[116:117] op_sel_hi:[1,0,1]
	v_pk_fma_f32 v[80:81], v[114:115], v[4:5], v[56:57] op_sel_hi:[1,0,1]
	v_mov_b32_e32 v4, v63
	v_pk_fma_f32 v[64:65], v[112:113], v[4:5], v[118:119] op_sel_hi:[1,0,1]
	v_pk_fma_f32 v[68:69], v[114:115], v[4:5], v[60:61] op_sel_hi:[1,0,1]
	v_mov_b32_e32 v4, v67
	v_pk_fma_f32 v[60:61], v[112:113], v[4:5], v[120:121] op_sel_hi:[1,0,1]
	v_pk_fma_f32 v[62:63], v[114:115], v[4:5], v[154:155] op_sel_hi:[1,0,1]
	v_mov_b32_e32 v4, v71
	v_pk_fma_f32 v[56:57], v[112:113], v[4:5], v[156:157] op_sel_hi:[1,0,1]
	v_pk_fma_f32 v[58:59], v[114:115], v[4:5], v[158:159] op_sel_hi:[1,0,1]
	v_add_co_u32_e32 v4, vcc, s24, v106
	ds_read_b128 v[8:11], v72 offset:2064
	ds_read_b128 v[120:123], v72 offset:32784
	v_addc_co_u32_e32 v5, vcc, 0, v107, vcc
	ds_read_b128 v[112:115], v72 offset:26640
	ds_read_b128 v[116:119], v72 offset:30736
	s_mov_b32 s24, 0x1e000
	s_waitcnt vmcnt(0) lgkmcnt(3)
	v_mov_b64_e32 v[4:5], v[196:197]
	v_mov_b64_e32 v[6:7], v[198:199]
	v_pk_fma_f32 v[124:125], v[4:5], v[8:9], v[12:13] op_sel_hi:[1,0,1]
	ds_read_b128 v[12:15], v72 offset:4112
	s_waitcnt lgkmcnt(2)
	v_pk_fma_f32 v[154:155], v[4:5], v[112:113], v[78:79] op_sel_hi:[1,0,1]
	v_pk_fma_f32 v[156:157], v[6:7], v[112:113], v[80:81] op_sel_hi:[1,0,1]
	ds_read_b128 v[78:81], v72 offset:28688
	v_pk_fma_f32 v[66:67], v[4:5], v[0:1], v[160:161] op_sel_hi:[1,0,1]
	s_waitcnt lgkmcnt(1)
	v_pk_fma_f32 v[126:127], v[4:5], v[12:13], v[16:17] op_sel_hi:[1,0,1]
	ds_read_b128 v[16:19], v72 offset:6160
	v_pk_fma_f32 v[60:61], v[4:5], v[116:117], v[60:61] op_sel_hi:[1,0,1]
	s_waitcnt lgkmcnt(1)
	v_pk_fma_f32 v[64:65], v[4:5], v[78:79], v[64:65] op_sel_hi:[1,0,1]
	v_pk_fma_f32 v[56:57], v[4:5], v[120:121], v[56:57] op_sel_hi:[1,0,1]
	v_pk_fma_f32 v[70:71], v[6:7], v[0:1], v[162:163] op_sel_hi:[1,0,1]
	s_waitcnt lgkmcnt(0)
	v_pk_fma_f32 v[128:129], v[4:5], v[16:17], v[20:21] op_sel_hi:[1,0,1]
	ds_read_b128 v[20:23], v72 offset:8208
	v_pk_fma_f32 v[108:109], v[6:7], v[8:9], v[108:109] op_sel_hi:[1,0,1]
	v_pk_fma_f32 v[104:105], v[6:7], v[12:13], v[104:105] op_sel_hi:[1,0,1]
	v_pk_fma_f32 v[102:103], v[6:7], v[16:17], v[102:103] op_sel_hi:[1,0,1]
	v_pk_fma_f32 v[68:69], v[6:7], v[78:79], v[68:69] op_sel_hi:[1,0,1]
	s_waitcnt lgkmcnt(0)
	v_pk_fma_f32 v[130:131], v[4:5], v[20:21], v[24:25] op_sel_hi:[1,0,1]
	ds_read_b128 v[24:27], v72 offset:10256
	v_pk_fma_f32 v[100:101], v[6:7], v[20:21], v[100:101] op_sel_hi:[1,0,1]
	v_pk_fma_f32 v[62:63], v[6:7], v[116:117], v[62:63] op_sel_hi:[1,0,1]
	v_pk_fma_f32 v[58:59], v[6:7], v[120:121], v[58:59] op_sel_hi:[1,0,1]
	s_waitcnt lgkmcnt(0)
	v_pk_fma_f32 v[132:133], v[4:5], v[24:25], v[28:29] op_sel_hi:[1,0,1]
	ds_read_b128 v[28:31], v72 offset:12304
	v_pk_fma_f32 v[98:99], v[6:7], v[24:25], v[98:99] op_sel_hi:[1,0,1]
	s_waitcnt lgkmcnt(0)
	v_pk_fma_f32 v[134:135], v[4:5], v[28:29], v[32:33] op_sel_hi:[1,0,1]
	ds_read_b128 v[32:35], v72 offset:14352
	v_pk_fma_f32 v[96:97], v[6:7], v[28:29], v[96:97] op_sel_hi:[1,0,1]
	s_waitcnt lgkmcnt(0)
	v_pk_fma_f32 v[136:137], v[4:5], v[32:33], v[36:37] op_sel_hi:[1,0,1]
	ds_read_b128 v[36:39], v72 offset:16400
	v_pk_fma_f32 v[94:95], v[6:7], v[32:33], v[94:95] op_sel_hi:[1,0,1]
	s_waitcnt lgkmcnt(0)
	v_pk_fma_f32 v[146:147], v[4:5], v[36:37], v[40:41] op_sel_hi:[1,0,1]
	ds_read_b128 v[40:43], v72 offset:18448
	v_pk_fma_f32 v[92:93], v[6:7], v[36:37], v[92:93] op_sel_hi:[1,0,1]
	s_waitcnt lgkmcnt(0)
	v_pk_fma_f32 v[148:149], v[4:5], v[40:41], v[44:45] op_sel_hi:[1,0,1]
	ds_read_b128 v[44:47], v72 offset:20496
	v_pk_fma_f32 v[90:91], v[6:7], v[40:41], v[90:91] op_sel_hi:[1,0,1]
	s_waitcnt lgkmcnt(0)
	v_pk_fma_f32 v[150:151], v[4:5], v[44:45], v[48:49] op_sel_hi:[1,0,1]
	ds_read_b128 v[48:51], v72 offset:22544
	v_pk_fma_f32 v[88:89], v[6:7], v[44:45], v[88:89] op_sel_hi:[1,0,1]
	s_waitcnt lgkmcnt(0)
	v_pk_fma_f32 v[152:153], v[4:5], v[48:49], v[52:53] op_sel_hi:[1,0,1]
	ds_read_b128 v[52:55], v72 offset:24592
	v_pk_fma_f32 v[86:87], v[6:7], v[48:49], v[86:87] op_sel_hi:[1,0,1]
	v_add_u32_e32 v72, 32, v72
	s_waitcnt lgkmcnt(0)
	v_pk_fma_f32 v[82:83], v[4:5], v[52:53], v[82:83] op_sel_hi:[1,0,1]
	v_add_co_u32_e32 v4, vcc, s24, v106
	v_pk_fma_f32 v[84:85], v[6:7], v[52:53], v[84:85] op_sel_hi:[1,0,1]
	s_nop 0
	v_addc_co_u32_e32 v5, vcc, 0, v107, vcc
	s_mov_b32 s24, 0x24000
	s_waitcnt vmcnt(0)
	v_mov_b64_e32 v[4:5], v[200:201]
	v_mov_b64_e32 v[6:7], v[202:203]
	v_pk_fma_f32 v[66:67], v[4:5], v[0:1], v[66:67] op_sel:[0,1,0]
	v_pk_fma_f32 v[0:1], v[6:7], v[0:1], v[70:71] op_sel:[0,1,0]
	v_pk_fma_f32 v[70:71], v[4:5], v[8:9], v[124:125] op_sel:[0,1,0]
	v_pk_fma_f32 v[8:9], v[6:7], v[8:9], v[108:109] op_sel:[0,1,0]
	v_pk_fma_f32 v[108:109], v[4:5], v[12:13], v[126:127] op_sel:[0,1,0]
	v_pk_fma_f32 v[12:13], v[6:7], v[12:13], v[104:105] op_sel:[0,1,0]
	v_pk_fma_f32 v[104:105], v[4:5], v[16:17], v[128:129] op_sel:[0,1,0]
	v_pk_fma_f32 v[16:17], v[6:7], v[16:17], v[102:103] op_sel:[0,1,0]
	v_pk_fma_f32 v[102:103], v[4:5], v[20:21], v[130:131] op_sel:[0,1,0]
	v_pk_fma_f32 v[20:21], v[6:7], v[20:21], v[100:101] op_sel:[0,1,0]
	v_pk_fma_f32 v[100:101], v[4:5], v[24:25], v[132:133] op_sel:[0,1,0]
	v_pk_fma_f32 v[24:25], v[6:7], v[24:25], v[98:99] op_sel:[0,1,0]
	v_pk_fma_f32 v[98:99], v[4:5], v[28:29], v[134:135] op_sel:[0,1,0]
	v_pk_fma_f32 v[28:29], v[6:7], v[28:29], v[96:97] op_sel:[0,1,0]
	v_pk_fma_f32 v[96:97], v[4:5], v[32:33], v[136:137] op_sel:[0,1,0]
	v_pk_fma_f32 v[32:33], v[6:7], v[32:33], v[94:95] op_sel:[0,1,0]
	v_pk_fma_f32 v[94:95], v[4:5], v[36:37], v[146:147] op_sel:[0,1,0]
	v_pk_fma_f32 v[36:37], v[6:7], v[36:37], v[92:93] op_sel:[0,1,0]
	v_pk_fma_f32 v[92:93], v[4:5], v[40:41], v[148:149] op_sel:[0,1,0]
	v_pk_fma_f32 v[40:41], v[6:7], v[40:41], v[90:91] op_sel:[0,1,0]
	v_pk_fma_f32 v[90:91], v[4:5], v[44:45], v[150:151] op_sel:[0,1,0]
	v_pk_fma_f32 v[44:45], v[6:7], v[44:45], v[88:89] op_sel:[0,1,0]
	v_pk_fma_f32 v[88:89], v[4:5], v[48:49], v[152:153] op_sel:[0,1,0]
	v_pk_fma_f32 v[82:83], v[4:5], v[52:53], v[82:83] op_sel:[0,1,0]
	v_pk_fma_f32 v[52:53], v[6:7], v[52:53], v[84:85] op_sel:[0,1,0]
	v_pk_fma_f32 v[84:85], v[4:5], v[112:113], v[154:155] op_sel:[0,1,0]
	v_pk_fma_f32 v[64:65], v[4:5], v[78:79], v[64:65] op_sel:[0,1,0]
	v_pk_fma_f32 v[60:61], v[4:5], v[116:117], v[60:61] op_sel:[0,1,0]
	v_pk_fma_f32 v[56:57], v[4:5], v[120:121], v[56:57] op_sel:[0,1,0]
	v_add_co_u32_e32 v4, vcc, s24, v106
	v_pk_fma_f32 v[48:49], v[6:7], v[48:49], v[86:87] op_sel:[0,1,0]
	s_nop 0
	v_addc_co_u32_e32 v5, vcc, 0, v107, vcc
	v_pk_fma_f32 v[86:87], v[6:7], v[112:113], v[156:157] op_sel:[0,1,0]
	v_pk_fma_f32 v[68:69], v[6:7], v[78:79], v[68:69] op_sel:[0,1,0]
	v_pk_fma_f32 v[62:63], v[6:7], v[116:117], v[62:63] op_sel:[0,1,0]
	v_pk_fma_f32 v[58:59], v[6:7], v[120:121], v[58:59] op_sel:[0,1,0]
	s_mov_b32 s24, 0x2a000
	s_waitcnt vmcnt(0)
	v_mov_b64_e32 v[4:5], v[204:205]
	v_mov_b64_e32 v[6:7], v[206:207]
	v_pk_fma_f32 v[66:67], v[4:5], v[2:3], v[66:67] op_sel_hi:[1,0,1]
	v_pk_fma_f32 v[70:71], v[4:5], v[10:11], v[70:71] op_sel_hi:[1,0,1]
	v_pk_fma_f32 v[108:109], v[4:5], v[14:15], v[108:109] op_sel_hi:[1,0,1]
	v_pk_fma_f32 v[116:117], v[4:5], v[18:19], v[104:105] op_sel_hi:[1,0,1]
	v_pk_fma_f32 v[124:125], v[4:5], v[22:23], v[102:103] op_sel_hi:[1,0,1]
	v_pk_fma_f32 v[128:129], v[4:5], v[26:27], v[100:101] op_sel_hi:[1,0,1]
	v_pk_fma_f32 v[132:133], v[4:5], v[30:31], v[98:99] op_sel_hi:[1,0,1]
	v_pk_fma_f32 v[136:137], v[4:5], v[34:35], v[96:97] op_sel_hi:[1,0,1]
	v_pk_fma_f32 v[148:149], v[4:5], v[38:39], v[94:95] op_sel_hi:[1,0,1]
	v_pk_fma_f32 v[152:153], v[4:5], v[42:43], v[92:93] op_sel_hi:[1,0,1]
	v_pk_fma_f32 v[156:157], v[4:5], v[46:47], v[90:91] op_sel_hi:[1,0,1]
	v_pk_fma_f32 v[160:161], v[4:5], v[50:51], v[88:89] op_sel_hi:[1,0,1]
	v_pk_fma_f32 v[164:165], v[4:5], v[54:55], v[82:83] op_sel_hi:[1,0,1]
	v_pk_fma_f32 v[168:169], v[4:5], v[114:115], v[84:85] op_sel_hi:[1,0,1]
	v_pk_fma_f32 v[64:65], v[4:5], v[80:81], v[64:65] op_sel_hi:[1,0,1]
	v_pk_fma_f32 v[172:173], v[4:5], v[118:119], v[60:61] op_sel_hi:[1,0,1]
	v_pk_fma_f32 v[176:177], v[4:5], v[122:123], v[56:57] op_sel_hi:[1,0,1]
	v_add_co_u32_e32 v4, vcc, s24, v106
	v_pk_fma_f32 v[0:1], v[6:7], v[2:3], v[0:1] op_sel_hi:[1,0,1]
	s_nop 0
	v_addc_co_u32_e32 v5, vcc, 0, v107, vcc
	v_pk_fma_f32 v[78:79], v[6:7], v[10:11], v[8:9] op_sel_hi:[1,0,1]
	v_pk_fma_f32 v[112:113], v[6:7], v[14:15], v[12:13] op_sel_hi:[1,0,1]
	v_pk_fma_f32 v[120:121], v[6:7], v[18:19], v[16:17] op_sel_hi:[1,0,1]
	v_pk_fma_f32 v[126:127], v[6:7], v[22:23], v[20:21] op_sel_hi:[1,0,1]
	v_pk_fma_f32 v[130:131], v[6:7], v[26:27], v[24:25] op_sel_hi:[1,0,1]
	v_pk_fma_f32 v[134:135], v[6:7], v[30:31], v[28:29] op_sel_hi:[1,0,1]
	v_pk_fma_f32 v[146:147], v[6:7], v[34:35], v[32:33] op_sel_hi:[1,0,1]
	v_pk_fma_f32 v[150:151], v[6:7], v[38:39], v[36:37] op_sel_hi:[1,0,1]
	v_pk_fma_f32 v[154:155], v[6:7], v[42:43], v[40:41] op_sel_hi:[1,0,1]
	v_pk_fma_f32 v[158:159], v[6:7], v[46:47], v[44:45] op_sel_hi:[1,0,1]
	v_pk_fma_f32 v[162:163], v[6:7], v[50:51], v[48:49] op_sel_hi:[1,0,1]
	v_pk_fma_f32 v[166:167], v[6:7], v[54:55], v[52:53] op_sel_hi:[1,0,1]
	v_pk_fma_f32 v[170:171], v[6:7], v[114:115], v[86:87] op_sel_hi:[1,0,1]
	v_pk_fma_f32 v[68:69], v[6:7], v[80:81], v[68:69] op_sel_hi:[1,0,1]
	v_pk_fma_f32 v[174:175], v[6:7], v[118:119], v[62:63] op_sel_hi:[1,0,1]
	v_pk_fma_f32 v[178:179], v[6:7], v[122:123], v[58:59] op_sel_hi:[1,0,1]
	v_mov_b32_e32 v2, v3
	s_waitcnt vmcnt(0)
	v_mov_b64_e32 v[4:5], v[208:209]
	v_mov_b64_e32 v[6:7], v[210:211]
	v_pk_fma_f32 v[8:9], v[6:7], v[2:3], v[0:1] op_sel_hi:[1,0,1]
	v_mov_b32_e32 v0, v11
	v_pk_fma_f32 v[102:103], v[4:5], v[0:1], v[70:71] op_sel_hi:[1,0,1]
	v_pk_fma_f32 v[12:13], v[6:7], v[0:1], v[78:79] op_sel_hi:[1,0,1]
	v_mov_b32_e32 v0, v15
	v_pk_fma_f32 v[100:101], v[4:5], v[0:1], v[108:109] op_sel_hi:[1,0,1]
	v_pk_fma_f32 v[16:17], v[6:7], v[0:1], v[112:113] op_sel_hi:[1,0,1]
	v_mov_b32_e32 v0, v19
	v_pk_fma_f32 v[98:99], v[4:5], v[0:1], v[116:117] op_sel_hi:[1,0,1]
	v_pk_fma_f32 v[20:21], v[6:7], v[0:1], v[120:121] op_sel_hi:[1,0,1]
	v_mov_b32_e32 v0, v23
	v_pk_fma_f32 v[96:97], v[4:5], v[0:1], v[124:125] op_sel_hi:[1,0,1]
	v_pk_fma_f32 v[24:25], v[6:7], v[0:1], v[126:127] op_sel_hi:[1,0,1]
	v_mov_b32_e32 v0, v27
	v_pk_fma_f32 v[94:95], v[4:5], v[0:1], v[128:129] op_sel_hi:[1,0,1]
	v_pk_fma_f32 v[28:29], v[6:7], v[0:1], v[130:131] op_sel_hi:[1,0,1]
	v_mov_b32_e32 v0, v31
	v_pk_fma_f32 v[92:93], v[4:5], v[0:1], v[132:133] op_sel_hi:[1,0,1]
	v_pk_fma_f32 v[32:33], v[6:7], v[0:1], v[134:135] op_sel_hi:[1,0,1]
	v_mov_b32_e32 v0, v35
	v_pk_fma_f32 v[90:91], v[4:5], v[0:1], v[136:137] op_sel_hi:[1,0,1]
	v_pk_fma_f32 v[36:37], v[6:7], v[0:1], v[146:147] op_sel_hi:[1,0,1]
	v_mov_b32_e32 v0, v39
	v_pk_fma_f32 v[88:89], v[4:5], v[0:1], v[148:149] op_sel_hi:[1,0,1]
	v_pk_fma_f32 v[40:41], v[6:7], v[0:1], v[150:151] op_sel_hi:[1,0,1]
	v_mov_b32_e32 v0, v43
	v_pk_fma_f32 v[86:87], v[4:5], v[0:1], v[152:153] op_sel_hi:[1,0,1]
	v_pk_fma_f32 v[44:45], v[6:7], v[0:1], v[154:155] op_sel_hi:[1,0,1]
	v_mov_b32_e32 v0, v47
	v_pk_fma_f32 v[84:85], v[4:5], v[0:1], v[156:157] op_sel_hi:[1,0,1]
	v_pk_fma_f32 v[48:49], v[6:7], v[0:1], v[158:159] op_sel_hi:[1,0,1]
	v_mov_b32_e32 v0, v51
	v_pk_fma_f32 v[82:83], v[4:5], v[0:1], v[160:161] op_sel_hi:[1,0,1]
	v_pk_fma_f32 v[52:53], v[6:7], v[0:1], v[162:163] op_sel_hi:[1,0,1]
	v_mov_b32_e32 v0, v55
	v_pk_fma_f32 v[58:59], v[4:5], v[0:1], v[164:165] op_sel_hi:[1,0,1]
	v_pk_fma_f32 v[56:57], v[6:7], v[0:1], v[166:167] op_sel_hi:[1,0,1]
	v_mov_b32_e32 v0, v115
	v_pk_fma_f32 v[62:63], v[4:5], v[0:1], v[168:169] op_sel_hi:[1,0,1]
	v_pk_fma_f32 v[60:61], v[6:7], v[0:1], v[170:171] op_sel_hi:[1,0,1]
	v_mov_b32_e32 v0, v81
	v_pk_fma_f32 v[104:105], v[4:5], v[2:3], v[66:67] op_sel_hi:[1,0,1]
	v_pk_fma_f32 v[66:67], v[4:5], v[0:1], v[64:65] op_sel_hi:[1,0,1]
	v_pk_fma_f32 v[64:65], v[6:7], v[0:1], v[68:69] op_sel_hi:[1,0,1]
	v_mov_b32_e32 v0, v119
	v_pk_fma_f32 v[70:71], v[4:5], v[0:1], v[172:173] op_sel_hi:[1,0,1]
	v_pk_fma_f32 v[68:69], v[6:7], v[0:1], v[174:175] op_sel_hi:[1,0,1]
	v_mov_b32_e32 v0, v123
	v_pk_fma_f32 v[80:81], v[4:5], v[0:1], v[176:177] op_sel_hi:[1,0,1]
	v_pk_fma_f32 v[78:79], v[6:7], v[0:1], v[178:179] op_sel_hi:[1,0,1]
	s_movk_i32 s76, 0x200
	s_mov_b64 s[68:69], 0
	s_and_b64 vcc, exec, s[6:7]
	s_cbranch_vccz .LBB0_139
	v_and_b32_e32 v1, 64, v138
	v_xor_b32_e32 v0, 16, v138
	v_add_u32_e32 v2, 64, v1
	v_cmp_lt_i32_e32 vcc, v0, v2
	v_xor_b32_e32 v3, 32, v138
	v_and_b32_e32 v72, 48, v139
	v_cndmask_b32_e32 v0, v138, v0, vcc
	v_lshlrev_b32_e32 v137, 2, v0
	ds_bpermute_b32 v4, v137, v8
	ds_bpermute_b32 v5, v137, v9
	ds_bpermute_b32 v0, v137, v104
	ds_bpermute_b32 v1, v137, v105
	ds_bpermute_b32 v18, v137, v100
	ds_bpermute_b32 v19, v137, v101
	s_waitcnt lgkmcnt(4)
	v_pk_add_f32 v[4:5], v[8:9], v[4:5]
	ds_bpermute_b32 v8, v137, v102
	ds_bpermute_b32 v9, v137, v103
	ds_bpermute_b32 v30, v137, v98
	ds_bpermute_b32 v31, v137, v99
	ds_bpermute_b32 v42, v137, v96
	ds_bpermute_b32 v43, v137, v97
	ds_bpermute_b32 v54, v137, v94
	ds_bpermute_b32 v55, v137, v95
	s_waitcnt lgkmcnt(10)
	v_pk_add_f32 v[0:1], v[104:105], v[0:1]
	ds_bpermute_b32 v14, v137, v12
	ds_bpermute_b32 v15, v137, v13
	s_waitcnt lgkmcnt(8)
	v_pk_add_f32 v[8:9], v[102:103], v[8:9]
	ds_bpermute_b32 v26, v137, v16
	ds_bpermute_b32 v27, v137, v17
	v_pk_add_f32 v[18:19], v[100:101], v[18:19]
	ds_bpermute_b32 v38, v137, v20
	ds_bpermute_b32 v39, v137, v21
	s_waitcnt lgkmcnt(10)
	v_pk_add_f32 v[30:31], v[98:99], v[30:31]
	ds_bpermute_b32 v50, v137, v24
	ds_bpermute_b32 v51, v137, v25
	s_waitcnt lgkmcnt(10)
	v_pk_add_f32 v[42:43], v[96:97], v[42:43]
	ds_bpermute_b32 v76, v137, v28
	ds_bpermute_b32 v77, v137, v29
	s_waitcnt lgkmcnt(10)
	v_pk_add_f32 v[54:55], v[94:95], v[54:55]
	ds_bpermute_b32 v94, v137, v92
	ds_bpermute_b32 v95, v137, v93
	ds_bpermute_b32 v96, v137, v32
	ds_bpermute_b32 v97, v137, v33
	ds_bpermute_b32 v98, v137, v90
	ds_bpermute_b32 v99, v137, v91
	ds_bpermute_b32 v100, v137, v36
	ds_bpermute_b32 v101, v137, v37
	ds_bpermute_b32 v102, v137, v88
	ds_bpermute_b32 v103, v137, v89
	ds_bpermute_b32 v104, v137, v40
	ds_bpermute_b32 v105, v137, v41
	ds_bpermute_b32 v106, v137, v86
	ds_bpermute_b32 v107, v137, v87
	ds_bpermute_b32 v108, v137, v44
	ds_bpermute_b32 v109, v137, v45
	ds_bpermute_b32 v110, v137, v84
	ds_bpermute_b32 v111, v137, v85
	ds_bpermute_b32 v112, v137, v48
	ds_bpermute_b32 v113, v137, v49
	ds_bpermute_b32 v114, v137, v82
	ds_bpermute_b32 v115, v137, v83
	ds_bpermute_b32 v116, v137, v52
	ds_bpermute_b32 v117, v137, v53
	ds_bpermute_b32 v118, v137, v58
	ds_bpermute_b32 v119, v137, v59
	ds_bpermute_b32 v120, v137, v56
	ds_bpermute_b32 v121, v137, v57
	ds_bpermute_b32 v122, v137, v62
	ds_bpermute_b32 v123, v137, v63
	ds_bpermute_b32 v124, v137, v60
	ds_bpermute_b32 v125, v137, v61
	ds_bpermute_b32 v126, v137, v66
	ds_bpermute_b32 v127, v137, v67
	ds_bpermute_b32 v128, v137, v64
	ds_bpermute_b32 v129, v137, v65
	ds_bpermute_b32 v130, v137, v70
	ds_bpermute_b32 v131, v137, v71
	ds_bpermute_b32 v132, v137, v68
	ds_bpermute_b32 v133, v137, v69
	ds_bpermute_b32 v134, v137, v80
	ds_bpermute_b32 v135, v137, v81
	ds_bpermute_b32 v136, v137, v78
	ds_bpermute_b32 v137, v137, v79
	v_cmp_lt_i32_e32 vcc, v3, v2
	s_waitcnt lgkmcnt(14)
	v_pk_add_f32 v[12:13], v[12:13], v[14:15]
	v_pk_add_f32 v[16:17], v[16:17], v[26:27]
	v_cndmask_b32_e32 v2, v138, v3, vcc
	v_lshlrev_b32_e32 v146, 2, v2
	v_pk_add_f32 v[20:21], v[20:21], v[38:39]
	v_pk_add_f32 v[24:25], v[24:25], v[50:51]
	v_pk_add_f32 v[28:29], v[28:29], v[76:77]
	v_pk_add_f32 v[92:93], v[92:93], v[94:95]
	v_pk_add_f32 v[32:33], v[32:33], v[96:97]
	v_pk_add_f32 v[90:91], v[90:91], v[98:99]
	v_pk_add_f32 v[36:37], v[36:37], v[100:101]
	v_pk_add_f32 v[88:89], v[88:89], v[102:103]
	v_pk_add_f32 v[40:41], v[40:41], v[104:105]
	v_pk_add_f32 v[86:87], v[86:87], v[106:107]
	v_pk_add_f32 v[44:45], v[44:45], v[108:109]
	v_pk_add_f32 v[84:85], v[84:85], v[110:111]
	v_pk_add_f32 v[48:49], v[48:49], v[112:113]
	v_pk_add_f32 v[82:83], v[82:83], v[114:115]
	v_pk_add_f32 v[52:53], v[52:53], v[116:117]
	v_pk_add_f32 v[58:59], v[58:59], v[118:119]
	v_pk_add_f32 v[56:57], v[56:57], v[120:121]
	v_pk_add_f32 v[62:63], v[62:63], v[122:123]
	s_waitcnt lgkmcnt(12)
	v_pk_add_f32 v[60:61], v[60:61], v[124:125]
	s_waitcnt lgkmcnt(10)
	v_pk_add_f32 v[66:67], v[66:67], v[126:127]
	s_waitcnt lgkmcnt(8)
	v_pk_add_f32 v[64:65], v[64:65], v[128:129]
	s_waitcnt lgkmcnt(6)
	v_pk_add_f32 v[70:71], v[70:71], v[130:131]
	s_waitcnt lgkmcnt(4)
	v_pk_add_f32 v[68:69], v[68:69], v[132:133]
	s_waitcnt lgkmcnt(2)
	v_pk_add_f32 v[80:81], v[80:81], v[134:135]
	s_waitcnt lgkmcnt(0)
	v_pk_add_f32 v[78:79], v[78:79], v[136:137]
	ds_bpermute_b32 v2, v146, v0
	ds_bpermute_b32 v3, v146, v1
	ds_bpermute_b32 v6, v146, v4
	ds_bpermute_b32 v7, v146, v5
	ds_bpermute_b32 v10, v146, v8
	ds_bpermute_b32 v11, v146, v9
	ds_bpermute_b32 v14, v146, v12
	ds_bpermute_b32 v15, v146, v13
	ds_bpermute_b32 v22, v146, v18
	ds_bpermute_b32 v23, v146, v19
	ds_bpermute_b32 v26, v146, v16
	ds_bpermute_b32 v27, v146, v17
	ds_bpermute_b32 v34, v146, v30
	ds_bpermute_b32 v35, v146, v31
	ds_bpermute_b32 v38, v146, v20
	ds_bpermute_b32 v39, v146, v21
	ds_bpermute_b32 v46, v146, v42
	ds_bpermute_b32 v47, v146, v43
	ds_bpermute_b32 v50, v146, v24
	ds_bpermute_b32 v51, v146, v25
	ds_bpermute_b32 v74, v146, v54
	ds_bpermute_b32 v75, v146, v55
	ds_bpermute_b32 v76, v146, v28
	ds_bpermute_b32 v77, v146, v29
	ds_bpermute_b32 v94, v146, v92
	ds_bpermute_b32 v95, v146, v93
	ds_bpermute_b32 v96, v146, v32
	ds_bpermute_b32 v97, v146, v33
	ds_bpermute_b32 v98, v146, v90
	ds_bpermute_b32 v99, v146, v91
	ds_bpermute_b32 v100, v146, v36
	ds_bpermute_b32 v101, v146, v37
	ds_bpermute_b32 v102, v146, v88
	ds_bpermute_b32 v103, v146, v89
	ds_bpermute_b32 v104, v146, v40
	ds_bpermute_b32 v105, v146, v41
	ds_bpermute_b32 v106, v146, v86
	ds_bpermute_b32 v107, v146, v87
	ds_bpermute_b32 v108, v146, v44
	ds_bpermute_b32 v109, v146, v45
	ds_bpermute_b32 v110, v146, v84
	ds_bpermute_b32 v111, v146, v85
	ds_bpermute_b32 v112, v146, v48
	ds_bpermute_b32 v113, v146, v49
	ds_bpermute_b32 v114, v146, v82
	ds_bpermute_b32 v115, v146, v83
	ds_bpermute_b32 v116, v146, v52
	ds_bpermute_b32 v117, v146, v53
	ds_bpermute_b32 v118, v146, v58
	ds_bpermute_b32 v119, v146, v59
	ds_bpermute_b32 v120, v146, v56
	ds_bpermute_b32 v121, v146, v57
	ds_bpermute_b32 v122, v146, v62
	ds_bpermute_b32 v123, v146, v63
	ds_bpermute_b32 v124, v146, v60
	ds_bpermute_b32 v125, v146, v61
	ds_bpermute_b32 v126, v146, v66
	ds_bpermute_b32 v127, v146, v67
	ds_bpermute_b32 v128, v146, v64
	ds_bpermute_b32 v129, v146, v65
	ds_bpermute_b32 v130, v146, v70
	ds_bpermute_b32 v131, v146, v71
	ds_bpermute_b32 v132, v146, v68
	ds_bpermute_b32 v133, v146, v69
	ds_bpermute_b32 v134, v146, v80
	ds_bpermute_b32 v135, v146, v81
	ds_bpermute_b32 v136, v146, v78
	ds_bpermute_b32 v137, v146, v79
	v_cmp_eq_u32_e32 vcc, 0, v72
	s_waitcnt lgkmcnt(0)
	s_barrier
	s_and_saveexec_b64 s[4:5], vcc
	s_cbranch_execz .LBB0_151
	v_lshrrev_b32_e32 v72, 6, v139
	s_movk_i32 s6, 0x1100
	v_mul_lo_u32 v72, v72, s6
	v_lshl_or_b32 v72, v141, 2, v72
	v_pk_add_f32 v[0:1], v[0:1], v[2:3]
	v_pk_add_f32 v[2:3], v[4:5], v[6:7]
	ds_write_b128 v72, v[0:3] offset:34816
	v_pk_add_f32 v[0:1], v[8:9], v[10:11]
	v_pk_add_f32 v[2:3], v[12:13], v[14:15]
	ds_write_b128 v72, v[0:3] offset:35072
	v_pk_add_f32 v[0:1], v[18:19], v[22:23]
	v_pk_add_f32 v[2:3], v[16:17], v[26:27]
	ds_write_b128 v72, v[0:3] offset:35328
	v_pk_add_f32 v[0:1], v[30:31], v[34:35]
	v_pk_add_f32 v[2:3], v[20:21], v[38:39]
	ds_write_b128 v72, v[0:3] offset:35584
	v_pk_add_f32 v[0:1], v[42:43], v[46:47]
	v_pk_add_f32 v[2:3], v[24:25], v[50:51]
	ds_write_b128 v72, v[0:3] offset:35840
	v_pk_add_f32 v[0:1], v[54:55], v[74:75]
	v_pk_add_f32 v[2:3], v[28:29], v[76:77]
	ds_write_b128 v72, v[0:3] offset:36096
	v_pk_add_f32 v[0:1], v[92:93], v[94:95]
	v_pk_add_f32 v[2:3], v[32:33], v[96:97]
	ds_write_b128 v72, v[0:3] offset:36352
	v_pk_add_f32 v[0:1], v[90:91], v[98:99]
	v_pk_add_f32 v[2:3], v[36:37], v[100:101]
	ds_write_b128 v72, v[0:3] offset:36608
	v_pk_add_f32 v[0:1], v[88:89], v[102:103]
	v_pk_add_f32 v[2:3], v[40:41], v[104:105]
	ds_write_b128 v72, v[0:3] offset:36864
	v_pk_add_f32 v[0:1], v[86:87], v[106:107]
	v_pk_add_f32 v[2:3], v[44:45], v[108:109]
	ds_write_b128 v72, v[0:3] offset:37120
	v_pk_add_f32 v[0:1], v[84:85], v[110:111]
	v_pk_add_f32 v[2:3], v[48:49], v[112:113]
	ds_write_b128 v72, v[0:3] offset:37376
	v_pk_add_f32 v[0:1], v[82:83], v[114:115]
	v_pk_add_f32 v[2:3], v[52:53], v[116:117]
	ds_write_b128 v72, v[0:3] offset:37632
	v_pk_add_f32 v[0:1], v[58:59], v[118:119]
	v_pk_add_f32 v[2:3], v[56:57], v[120:121]
	ds_write_b128 v72, v[0:3] offset:37888
	v_pk_add_f32 v[0:1], v[62:63], v[122:123]
	v_pk_add_f32 v[2:3], v[60:61], v[124:125]
	ds_write_b128 v72, v[0:3] offset:38144
	v_pk_add_f32 v[0:1], v[66:67], v[126:127]
	v_pk_add_f32 v[2:3], v[64:65], v[128:129]
	ds_write_b128 v72, v[0:3] offset:38400
	v_pk_add_f32 v[0:1], v[70:71], v[130:131]
	v_pk_add_f32 v[2:3], v[68:69], v[132:133]
	ds_write_b128 v72, v[0:3] offset:38656
	v_pk_add_f32 v[0:1], v[80:81], v[134:135]
	v_pk_add_f32 v[2:3], v[78:79], v[136:137]
	ds_write_b128 v72, v[0:3] offset:38912
